# gate-up phases: wave halves run their epilogues one after the other (ALIGN barrier moved behind wr0 epilogue, wr1 extra barrier ahead of its epilogue) so each overlaps the other half's MFMA segment
# baseline (speedup 1.0000x reference)
; #define PG8_STAGE(bufoff, gbase, voff) do { _Pragma("unroll") for (int _i = 0; _i < 2; ++_i) \
;         __builtin_amdgcn_global_load_lds((const unsigned*)((const char*)(gbase) + (voff)[_i]), (LAS unsigned*)(lds + (bufoff) + ldsw + _i * 8192), 16, 0, 0); } while (0)
; #define PG8_LDA(dst, b, h) do { _Pragma("unroll") for (int m = 0; m < 4; ++m) _Pragma("unroll") for (int k = 0; k < 2; ++k) dst[m][k] = *(const LAS bf16x8*)(lds + PG8_SA(b, h) + aoff + m * 2048 + k * 1024); } while (0)
; #define PG8_LDB(dst, b, h) do { _Pragma("unroll") for (int n = 0; n < 2; ++n) _Pragma("unroll") for (int k = 0; k < 2; ++k) dst[n][k] = *(const LAS bf16x8*)(lds + PG8_SB(b, h) + boff + n * 2048 + k * 1024); } while (0)
; #define PG8_MMA(ai, bj, At, Bt) do { __builtin_amdgcn_s_setprio(1); _Pragma("unroll") for (int m = 0; m < 4; ++m) _Pragma("unroll") for (int n = 0; n < 2; ++n) _Pragma("unroll") for (int k = 0; k < 2; ++k) \
;         acc[ai][bj][m][n] = __builtin_amdgcn_mfma_f32_16x16x32_bf16(Bt[n][k], At[m][k], acc[ai][bj][m][n], 0, 0, 0); __builtin_amdgcn_s_setprio(0); } while (0)
; #define PG8_WAIT_V(n) asm volatile("s_waitcnt vmcnt(" #n ")" ::: "memory")
; #define PG8_WAIT_L(n) asm volatile("s_waitcnt lgkmcnt(" #n ")" ::: "memory")
; #define PG8_BAR __builtin_amdgcn_s_barrier()
; #define PG8_SCHED __builtin_amdgcn_sched_barrier(0)
; template <class Epi, class Sched>
; DI void gemm_phase(LAS unsigned char* lds, const Gemm g, const Sched& S, const Epi& E) {
;     ...
;         for (int t = 0; t < nt; t += 2) {
;             const bool last = (t == nt - 2);
;             const char* a1 = cA + (size_t)(t + 1) * kstep;
;             const char* a2 = last ? nA : cA + (size_t)(t + 2) * kstep; const char* b2 = last ? nB : cB + (size_t)(t + 2) * kstep;
;             const char* a3 = a2 + kstep; const char* b3 = b2 + kstep;
;             PG8_LDB(B0, 0, 0); PG8_LDB(B1, 0, 1); PG8_SCHED; PG8_LDA(At, 0, 0); PG8_STAGE(PG8_SA(1, 1), a1 + hstepA, voffA);
;             PG8_WAIT_V(8); PG8_WAIT_L(0); PG8_BAR; PG8_MMA(0, 0, At, B0); PG8_MMA(0, 1, At, B1); PG8_BAR; PG8_SCHED;
;             PG8_LDA(At, 0, 1); PG8_STAGE(PG8_SB(0, 0), b2, voffB); PG8_STAGE(PG8_SB(0, 1), b2 + hstepB, voffB); PG8_STAGE(PG8_SA(0, 0), a2, voffA);
;             PG8_WAIT_V(8); PG8_WAIT_L(0); PG8_BAR; PG8_MMA(1, 0, At, B0); PG8_MMA(1, 1, At, B1); PG8_BAR; PG8_SCHED;
.LBB0_179:
	ds_read_b128 v[168:171], v162
	ds_read_b128 v[172:175], v162 offset:1024
	ds_read_b128 v[176:179], v162 offset:2048
	ds_read_b128 v[180:183], v162 offset:3072
	ds_read_b128 v[186:189], v163
	ds_read_b128 v[190:193], v163 offset:1024
	ds_read_b128 v[194:197], v163 offset:2048
	ds_read_b128 v[198:201], v163 offset:3072
	s_add_u32 s42, s40, 0xfffc0080
	s_addc_u32 s43, s41, -1
	s_cmp_eq_u32 s65, 12
	s_cselect_b32 s45, s35, s43
	s_cselect_b32 s44, s61, s42
	s_cselect_b32 s43, s21, s64
	s_cselect_b32 s42, s62, s63
	v_lshl_add_u64 v[234:235], s[40:41], 0, v[138:139]
	s_add_i32 m0, s49, 0xc000
	ds_read_b128 v[202:205], v160
	ds_read_b128 v[206:209], v160 offset:1024
	ds_read_b128 v[210:213], v160 offset:2048
	ds_read_b128 v[214:217], v160 offset:3072
	ds_read_b128 v[218:221], v160 offset:4096
	ds_read_b128 v[222:225], v160 offset:5120
	ds_read_b128 v[226:229], v160 offset:6144
	ds_read_b128 v[230:233], v160 offset:7168
	global_load_lds_dwordx4 v[234:235], off
	v_lshl_add_u64 v[234:235], s[40:41], 0, v[140:141]
	s_add_i32 m0, s49, 0xe000
	s_nop 0
	global_load_lds_dwordx4 v[234:235], off
	s_waitcnt vmcnt(8)
	s_waitcnt lgkmcnt(0)
	s_barrier
	s_setprio 1
	v_mfma_f32_16x16x32_bf16 v[126:129], v[168:171], v[202:205], v[126:129]
	v_mfma_f32_16x16x32_bf16 v[118:121], v[176:179], v[202:205], v[118:121]
	v_mfma_f32_16x16x32_bf16 v[110:113], v[168:171], v[210:213], v[110:113]
	v_mfma_f32_16x16x32_bf16 v[102:105], v[176:179], v[210:213], v[102:105]
	v_mfma_f32_16x16x32_bf16 v[94:97], v[168:171], v[218:221], v[94:97]
	v_mfma_f32_16x16x32_bf16 v[86:89], v[176:179], v[218:221], v[86:89]
	v_mfma_f32_16x16x32_bf16 v[78:81], v[168:171], v[226:229], v[78:81]
	v_mfma_f32_16x16x32_bf16 v[70:73], v[176:179], v[226:229], v[70:73]
	v_mfma_f32_16x16x32_bf16 v[126:129], v[172:175], v[206:209], v[126:129]
	v_mfma_f32_16x16x32_bf16 v[118:121], v[180:183], v[206:209], v[118:121]
	v_mfma_f32_16x16x32_bf16 v[110:113], v[172:175], v[214:217], v[110:113]
	v_mfma_f32_16x16x32_bf16 v[102:105], v[180:183], v[214:217], v[102:105]
	v_mfma_f32_16x16x32_bf16 v[94:97], v[172:175], v[222:225], v[94:97]
	v_mfma_f32_16x16x32_bf16 v[86:89], v[180:183], v[222:225], v[86:89]
	v_mfma_f32_16x16x32_bf16 v[78:81], v[172:175], v[230:233], v[78:81]
	v_mfma_f32_16x16x32_bf16 v[70:73], v[180:183], v[230:233], v[70:73]
	v_mfma_f32_16x16x32_bf16 v[122:125], v[186:189], v[202:205], v[122:125]
	v_mfma_f32_16x16x32_bf16 v[114:117], v[194:197], v[202:205], v[114:117]
	v_mfma_f32_16x16x32_bf16 v[106:109], v[186:189], v[210:213], v[106:109]
	v_mfma_f32_16x16x32_bf16 v[98:101], v[194:197], v[210:213], v[98:101]
	v_mfma_f32_16x16x32_bf16 v[90:93], v[186:189], v[218:221], v[90:93]
	v_mfma_f32_16x16x32_bf16 v[82:85], v[194:197], v[218:221], v[82:85]
	v_mfma_f32_16x16x32_bf16 v[74:77], v[186:189], v[226:229], v[74:77]
	v_mfma_f32_16x16x32_bf16 v[66:69], v[194:197], v[226:229], v[66:69]
	v_mfma_f32_16x16x32_bf16 v[122:125], v[190:193], v[206:209], v[122:125]
	v_mfma_f32_16x16x32_bf16 v[114:117], v[198:201], v[206:209], v[114:117]
	v_mfma_f32_16x16x32_bf16 v[106:109], v[190:193], v[214:217], v[106:109]
	v_mfma_f32_16x16x32_bf16 v[98:101], v[198:201], v[214:217], v[98:101]
	v_mfma_f32_16x16x32_bf16 v[90:93], v[190:193], v[222:225], v[90:93]
	v_mfma_f32_16x16x32_bf16 v[82:85], v[198:201], v[222:225], v[82:85]
	v_mfma_f32_16x16x32_bf16 v[74:77], v[190:193], v[230:233], v[74:77]
	v_mfma_f32_16x16x32_bf16 v[66:69], v[198:201], v[230:233], v[66:69]
	s_setprio 0
	s_barrier
	s_add_i32 s66, s57, s46
	v_lshl_add_u64 v[234:235], s[42:43], 0, v[134:135]
	s_mov_b32 m0, s66
	ds_read_b128 v[202:205], v160 offset:16384
	ds_read_b128 v[206:209], v160 offset:17408
	ds_read_b128 v[210:213], v160 offset:18432
	ds_read_b128 v[214:217], v160 offset:19456
	ds_read_b128 v[218:221], v160 offset:20480
	ds_read_b128 v[222:225], v160 offset:21504
	ds_read_b128 v[226:229], v160 offset:22528
	ds_read_b128 v[230:233], v160 offset:23552
	global_load_lds_dwordx4 v[234:235], off
	s_add_i32 m0, s66, 0x2000
	s_add_u32 s66, s42, 0x40000
	v_lshl_add_u64 v[236:237], s[42:43], 0, v[130:131]
	s_addc_u32 s67, s43, 0
	s_add_i32 s68, s58, s46
	global_load_lds_dwordx4 v[236:237], off
	v_lshl_add_u64 v[238:239], s[66:67], 0, v[134:135]
	s_mov_b32 m0, s68
	v_lshl_add_u64 v[240:241], s[44:45], 0, v[132:133]
	global_load_lds_dwordx4 v[238:239], off
	v_lshl_add_u64 v[238:239], s[66:67], 0, v[130:131]
	s_add_i32 m0, s68, 0x2000
	s_nop 0
	global_load_lds_dwordx4 v[238:239], off
	v_lshl_add_u64 v[238:239], s[44:45], 0, v[136:137]
	s_mov_b32 m0, s49
	s_nop 0
	global_load_lds_dwordx4 v[238:239], off
	s_mov_b32 m0, s50
	s_nop 0
	global_load_lds_dwordx4 v[240:241], off
	s_waitcnt vmcnt(8)
	s_waitcnt lgkmcnt(0)
	s_barrier
; #define PG8_STAGE(bufoff, gbase, voff) do { _Pragma("unroll") for (int _i = 0; _i < 2; ++_i) \
;         __builtin_amdgcn_global_load_lds((const unsigned*)((const char*)(gbase) + (voff)[_i]), (LAS unsigned*)(lds + (bufoff) + ldsw + _i * 8192), 16, 0, 0); } while (0)
; #define PG8_LDA(dst, b, h) do { _Pragma("unroll") for (int m = 0; m < 4; ++m) _Pragma("unroll") for (int k = 0; k < 2; ++k) dst[m][k] = *(const LAS bf16x8*)(lds + PG8_SA(b, h) + aoff + m * 2048 + k * 1024); } while (0)
; #define PG8_LDB(dst, b, h) do { _Pragma("unroll") for (int n = 0; n < 2; ++n) _Pragma("unroll") for (int k = 0; k < 2; ++k) dst[n][k] = *(const LAS bf16x8*)(lds + PG8_SB(b, h) + boff + n * 2048 + k * 1024); } while (0)
; #define PG8_MMA(ai, bj, At, Bt) do { __builtin_amdgcn_s_setprio(1); _Pragma("unroll") for (int m = 0; m < 4; ++m) _Pragma("unroll") for (int n = 0; n < 2; ++n) _Pragma("unroll") for (int k = 0; k < 2; ++k) \
;         acc[ai][bj][m][n] = __builtin_amdgcn_mfma_f32_16x16x32_bf16(Bt[n][k], At[m][k], acc[ai][bj][m][n], 0, 0, 0); __builtin_amdgcn_s_setprio(0); } while (0)
; #define PG8_WAIT_V(n) asm volatile("s_waitcnt vmcnt(" #n ")" ::: "memory")
; #define PG8_WAIT_L(n) asm volatile("s_waitcnt lgkmcnt(" #n ")" ::: "memory")
; #define PG8_BAR __builtin_amdgcn_s_barrier()
; #define PG8_SCHED __builtin_amdgcn_sched_barrier(0)
; template <class Epi, class Sched>
; DI void gemm_phase(LAS unsigned char* lds, const Gemm g, const Sched& S, const Epi& E) {
;     ...
;             PG8_WAIT_V(8); PG8_WAIT_L(0); PG8_BAR; PG8_MMA(1, 0, At, B0); PG8_MMA(1, 1, At, B1); PG8_BAR; PG8_SCHED;
;             PG8_LDB(B0, 1, 0); PG8_LDB(B1, 1, 1); PG8_SCHED; PG8_LDA(At, 1, 0); PG8_STAGE(PG8_SA(0, 1), a2 + hstepA, voffA);
;             PG8_WAIT_V(8); PG8_WAIT_L(0); PG8_BAR; PG8_MMA(0, 0, At, B0); PG8_MMA(0, 1, At, B1); PG8_BAR; PG8_SCHED;
	s_setprio 1
	v_mfma_f32_16x16x32_bf16 v[62:65], v[168:171], v[202:205], v[62:65]
	v_mfma_f32_16x16x32_bf16 v[54:57], v[176:179], v[202:205], v[54:57]
	v_mfma_f32_16x16x32_bf16 v[46:49], v[168:171], v[210:213], v[46:49]
	v_mfma_f32_16x16x32_bf16 v[38:41], v[176:179], v[210:213], v[38:41]
	v_mfma_f32_16x16x32_bf16 v[30:33], v[168:171], v[218:221], v[30:33]
	v_mfma_f32_16x16x32_bf16 v[22:25], v[176:179], v[218:221], v[22:25]
	v_mfma_f32_16x16x32_bf16 v[14:17], v[168:171], v[226:229], v[14:17]
	v_mfma_f32_16x16x32_bf16 v[6:9], v[176:179], v[226:229], v[6:9]
	v_mfma_f32_16x16x32_bf16 v[62:65], v[172:175], v[206:209], v[62:65]
	v_mfma_f32_16x16x32_bf16 v[54:57], v[180:183], v[206:209], v[54:57]
	v_mfma_f32_16x16x32_bf16 v[46:49], v[172:175], v[214:217], v[46:49]
	v_mfma_f32_16x16x32_bf16 v[38:41], v[180:183], v[214:217], v[38:41]
	v_mfma_f32_16x16x32_bf16 v[30:33], v[172:175], v[222:225], v[30:33]
	v_mfma_f32_16x16x32_bf16 v[22:25], v[180:183], v[222:225], v[22:25]
	v_mfma_f32_16x16x32_bf16 v[14:17], v[172:175], v[230:233], v[14:17]
	v_mfma_f32_16x16x32_bf16 v[6:9], v[180:183], v[230:233], v[6:9]
	v_mfma_f32_16x16x32_bf16 v[58:61], v[186:189], v[202:205], v[58:61]
	v_mfma_f32_16x16x32_bf16 v[50:53], v[194:197], v[202:205], v[50:53]
	v_mfma_f32_16x16x32_bf16 v[42:45], v[186:189], v[210:213], v[42:45]
	v_mfma_f32_16x16x32_bf16 v[34:37], v[194:197], v[210:213], v[34:37]
	v_mfma_f32_16x16x32_bf16 v[26:29], v[186:189], v[218:221], v[26:29]
	v_mfma_f32_16x16x32_bf16 v[18:21], v[194:197], v[218:221], v[18:21]
	v_mfma_f32_16x16x32_bf16 v[10:13], v[186:189], v[226:229], v[10:13]
	v_mfma_f32_16x16x32_bf16 v[2:5], v[194:197], v[226:229], v[2:5]
	v_mfma_f32_16x16x32_bf16 v[58:61], v[190:193], v[206:209], v[58:61]
	v_mfma_f32_16x16x32_bf16 v[50:53], v[198:201], v[206:209], v[50:53]
	v_mfma_f32_16x16x32_bf16 v[42:45], v[190:193], v[214:217], v[42:45]
	v_mfma_f32_16x16x32_bf16 v[34:37], v[198:201], v[214:217], v[34:37]
	v_mfma_f32_16x16x32_bf16 v[26:29], v[190:193], v[222:225], v[26:29]
	v_mfma_f32_16x16x32_bf16 v[18:21], v[198:201], v[222:225], v[18:21]
	v_mfma_f32_16x16x32_bf16 v[10:13], v[190:193], v[230:233], v[10:13]
	v_mfma_f32_16x16x32_bf16 v[2:5], v[198:201], v[230:233], v[2:5]
	s_setprio 0
	s_barrier
	s_add_i32 s66, 0, 0x18000
	v_add_u32_e32 v167, s66, v158
	s_add_i32 s67, 0, 0x1c000
	ds_read_b128 v[168:171], v167
	ds_read_b128 v[172:175], v167 offset:1024
	ds_read_b128 v[176:179], v167 offset:2048
	ds_read_b128 v[180:183], v167 offset:3072
	v_add_u32_e32 v167, s67, v158
	ds_read_b128 v[186:189], v167
	ds_read_b128 v[190:193], v167 offset:1024
	ds_read_b128 v[194:197], v167 offset:2048
	ds_read_b128 v[198:201], v167 offset:3072
	s_add_u32 s44, s44, 0x40000
	s_addc_u32 s45, s45, 0
	s_mov_b32 m0, s51
	v_lshl_add_u64 v[242:243], s[44:45], 0, v[136:137]
	ds_read_b128 v[202:205], v160 offset:32768
	ds_read_b128 v[206:209], v160 offset:33792
	ds_read_b128 v[210:213], v160 offset:34816
	ds_read_b128 v[214:217], v160 offset:35840
	ds_read_b128 v[218:221], v160 offset:36864
	ds_read_b128 v[222:225], v160 offset:37888
	ds_read_b128 v[226:229], v160 offset:38912
	ds_read_b128 v[230:233], v160 offset:39936
	global_load_lds_dwordx4 v[242:243], off
	v_lshl_add_u64 v[242:243], s[44:45], 0, v[132:133]
	s_mov_b32 m0, s52
	s_nop 0
	global_load_lds_dwordx4 v[242:243], off
	s_waitcnt vmcnt(8)
	s_waitcnt lgkmcnt(0)
	s_barrier
	s_setprio 1
	v_mfma_f32_16x16x32_bf16 v[126:129], v[168:171], v[202:205], v[126:129]
	v_mfma_f32_16x16x32_bf16 v[118:121], v[176:179], v[202:205], v[118:121]
	v_mfma_f32_16x16x32_bf16 v[110:113], v[168:171], v[210:213], v[110:113]
	v_mfma_f32_16x16x32_bf16 v[102:105], v[176:179], v[210:213], v[102:105]
	v_mfma_f32_16x16x32_bf16 v[94:97], v[168:171], v[218:221], v[94:97]
	v_mfma_f32_16x16x32_bf16 v[86:89], v[176:179], v[218:221], v[86:89]
	v_mfma_f32_16x16x32_bf16 v[78:81], v[168:171], v[226:229], v[78:81]
	v_mfma_f32_16x16x32_bf16 v[70:73], v[176:179], v[226:229], v[70:73]
	v_mfma_f32_16x16x32_bf16 v[126:129], v[172:175], v[206:209], v[126:129]
	v_mfma_f32_16x16x32_bf16 v[118:121], v[180:183], v[206:209], v[118:121]
	v_mfma_f32_16x16x32_bf16 v[110:113], v[172:175], v[214:217], v[110:113]
	v_mfma_f32_16x16x32_bf16 v[102:105], v[180:183], v[214:217], v[102:105]
	v_mfma_f32_16x16x32_bf16 v[94:97], v[172:175], v[222:225], v[94:97]
	v_mfma_f32_16x16x32_bf16 v[86:89], v[180:183], v[222:225], v[86:89]
	v_mfma_f32_16x16x32_bf16 v[78:81], v[172:175], v[230:233], v[78:81]
	v_mfma_f32_16x16x32_bf16 v[70:73], v[180:183], v[230:233], v[70:73]
	v_mfma_f32_16x16x32_bf16 v[122:125], v[186:189], v[202:205], v[122:125]
	v_mfma_f32_16x16x32_bf16 v[114:117], v[194:197], v[202:205], v[114:117]
	v_mfma_f32_16x16x32_bf16 v[106:109], v[186:189], v[210:213], v[106:109]
	v_mfma_f32_16x16x32_bf16 v[98:101], v[194:197], v[210:213], v[98:101]
	v_mfma_f32_16x16x32_bf16 v[90:93], v[186:189], v[218:221], v[90:93]
	v_mfma_f32_16x16x32_bf16 v[82:85], v[194:197], v[218:221], v[82:85]
	v_mfma_f32_16x16x32_bf16 v[74:77], v[186:189], v[226:229], v[74:77]
	v_mfma_f32_16x16x32_bf16 v[66:69], v[194:197], v[226:229], v[66:69]
	v_mfma_f32_16x16x32_bf16 v[122:125], v[190:193], v[206:209], v[122:125]
	v_mfma_f32_16x16x32_bf16 v[114:117], v[198:201], v[206:209], v[114:117]
	v_mfma_f32_16x16x32_bf16 v[106:109], v[190:193], v[214:217], v[106:109]
	v_mfma_f32_16x16x32_bf16 v[98:101], v[198:201], v[214:217], v[98:101]
	v_mfma_f32_16x16x32_bf16 v[90:93], v[190:193], v[222:225], v[90:93]
	v_mfma_f32_16x16x32_bf16 v[82:85], v[198:201], v[222:225], v[82:85]
	v_mfma_f32_16x16x32_bf16 v[74:77], v[190:193], v[230:233], v[74:77]
	v_mfma_f32_16x16x32_bf16 v[66:69], v[198:201], v[230:233], v[66:69]
	s_setprio 0
	s_barrier
; DI float fast_exp2(float x) { return __builtin_amdgcn_exp2f(x); }
; DI float fast_rcp(float x) { return __builtin_amdgcn_rcpf(x); }
; #define PG8_STAGE(bufoff, gbase, voff) do { _Pragma("unroll") for (int _i = 0; _i < 2; ++_i) \
;         __builtin_amdgcn_global_load_lds((const unsigned*)((const char*)(gbase) + (voff)[_i]), (LAS unsigned*)(lds + (bufoff) + ldsw + _i * 8192), 16, 0, 0); } while (0)
; #define PG8_LDA(dst, b, h) do { _Pragma("unroll") for (int m = 0; m < 4; ++m) _Pragma("unroll") for (int k = 0; k < 2; ++k) dst[m][k] = *(const LAS bf16x8*)(lds + PG8_SA(b, h) + aoff + m * 2048 + k * 1024); } while (0)
; #define PG8_MMA(ai, bj, At, Bt) do { __builtin_amdgcn_s_setprio(1); _Pragma("unroll") for (int m = 0; m < 4; ++m) _Pragma("unroll") for (int n = 0; n < 2; ++n) _Pragma("unroll") for (int k = 0; k < 2; ++k) \
;         acc[ai][bj][m][n] = __builtin_amdgcn_mfma_f32_16x16x32_bf16(Bt[n][k], At[m][k], acc[ai][bj][m][n], 0, 0, 0); __builtin_amdgcn_s_setprio(0); } while (0)
; #define PG8_WAIT_V(n) asm volatile("s_waitcnt vmcnt(" #n ")" ::: "memory")
; #define PG8_BAR __builtin_amdgcn_s_barrier()
; template <class Epi, class Sched>
; DI void gemm_phase(LAS unsigned char* lds, const Gemm g, const Sched& S, const Epi& E) {
;     ...
;             PG8_LDA(At, 1, 1); PG8_STAGE(PG8_SB(1, 0), b3, voffB); PG8_STAGE(PG8_SB(1, 1), b3 + hstepB, voffB); PG8_STAGE(PG8_SA(1, 0), a3, voffA);
;             PG8_WAIT_V(8); PG8_WAIT_L(0); PG8_BAR; PG8_MMA(1, 0, At, B0); PG8_MMA(1, 1, At, B1); PG8_BAR; PG8_SCHED;
;         }
;         if (wr == 0) PG8_BAR;
;     DI void operator()(Acc& acc, const pg8::Unit& u, int wr, int wc, int fr, int fq, const Pre& pr) const {
;         const int col = u.pn * 128 + wc * 32 + fq * 8;
; #pragma unroll
;         for (int ai = 0; ai < 2; ++ai)
; #pragma unroll
;             for (int m = 0; m < 4; ++m) {
;                 const int row = u.pm * 256 + ai * 128 + wr * 64 + m * 16 + fr;
;                 const float msq = msq_of(pr.v[ai * 4 + m]), nrl = -1.4426950408889634f * __builtin_amdgcn_rsqf(msq);
;                 f32x4 h[2];
; #pragma unroll
;                 for (int n = 0; n < 2; ++n)
; #pragma unroll
;                     for (int i = 0; i < 4; ++i) { const float ga = acc[ai][0][m][n][i], ua = acc[ai][1][m][n][i];
;                         const float e = fast_exp2(ga * nrl); h[n][i] = (ga * ua) * fast_rcp(__builtin_fmaf(e, msq, msq)); }
	s_add_i32 s44, s66, s46
	v_lshl_add_u64 v[234:235], v[234:235], 0, s[16:17]
	s_mov_b32 m0, s44
	ds_read_b128 v[202:205], v160 offset:49152
	ds_read_b128 v[206:209], v160 offset:50176
	ds_read_b128 v[210:213], v160 offset:51200
	ds_read_b128 v[214:217], v160 offset:52224
	ds_read_b128 v[218:221], v160 offset:53248
	ds_read_b128 v[222:225], v160 offset:54272
	ds_read_b128 v[226:229], v160 offset:55296
	ds_read_b128 v[230:233], v160 offset:56320
	global_load_lds_dwordx4 v[234:235], off
	s_add_i32 m0, s44, 0x2000
	s_add_u32 s42, s42, 0x40080
	v_lshl_add_u64 v[234:235], v[236:237], 0, s[16:17]
	s_addc_u32 s43, s43, 0
	s_add_i32 s44, s67, s46
	global_load_lds_dwordx4 v[234:235], off
	v_lshl_add_u64 v[234:235], s[42:43], 0, v[134:135]
	s_mov_b32 m0, s44
	s_nop 0
	global_load_lds_dwordx4 v[234:235], off
	v_lshl_add_u64 v[234:235], s[42:43], 0, v[130:131]
	s_add_i32 m0, s44, 0x2000
	s_nop 0
	global_load_lds_dwordx4 v[234:235], off
	v_lshl_add_u64 v[234:235], v[238:239], 0, s[16:17]
	s_mov_b32 m0, s54
	s_nop 0
	global_load_lds_dwordx4 v[234:235], off
	v_lshl_add_u64 v[234:235], v[240:241], 0, s[16:17]
	s_mov_b32 m0, s55
	s_nop 0
	global_load_lds_dwordx4 v[234:235], off
	s_waitcnt vmcnt(8)
	s_waitcnt lgkmcnt(0)
	s_barrier
	s_setprio 1
	v_mfma_f32_16x16x32_bf16 v[62:65], v[168:171], v[202:205], v[62:65]
	v_mfma_f32_16x16x32_bf16 v[54:57], v[176:179], v[202:205], v[54:57]
	v_mfma_f32_16x16x32_bf16 v[46:49], v[168:171], v[210:213], v[46:49]
	v_mfma_f32_16x16x32_bf16 v[38:41], v[176:179], v[210:213], v[38:41]
	v_mfma_f32_16x16x32_bf16 v[30:33], v[168:171], v[218:221], v[30:33]
	v_mfma_f32_16x16x32_bf16 v[22:25], v[176:179], v[218:221], v[22:25]
	v_mfma_f32_16x16x32_bf16 v[14:17], v[168:171], v[226:229], v[14:17]
	v_mfma_f32_16x16x32_bf16 v[6:9], v[176:179], v[226:229], v[6:9]
	v_mfma_f32_16x16x32_bf16 v[62:65], v[172:175], v[206:209], v[62:65]
	v_mfma_f32_16x16x32_bf16 v[54:57], v[180:183], v[206:209], v[54:57]
	v_mfma_f32_16x16x32_bf16 v[46:49], v[172:175], v[214:217], v[46:49]
	v_mfma_f32_16x16x32_bf16 v[38:41], v[180:183], v[214:217], v[38:41]
	v_mfma_f32_16x16x32_bf16 v[30:33], v[172:175], v[222:225], v[30:33]
	v_mfma_f32_16x16x32_bf16 v[22:25], v[180:183], v[222:225], v[22:25]
	v_mfma_f32_16x16x32_bf16 v[14:17], v[172:175], v[230:233], v[14:17]
	v_mfma_f32_16x16x32_bf16 v[6:9], v[180:183], v[230:233], v[6:9]
	v_mfma_f32_16x16x32_bf16 v[58:61], v[186:189], v[202:205], v[58:61]
	v_mfma_f32_16x16x32_bf16 v[50:53], v[194:197], v[202:205], v[50:53]
	v_mfma_f32_16x16x32_bf16 v[42:45], v[186:189], v[210:213], v[42:45]
	v_mfma_f32_16x16x32_bf16 v[34:37], v[194:197], v[210:213], v[34:37]
	v_mfma_f32_16x16x32_bf16 v[26:29], v[186:189], v[218:221], v[26:29]
	v_mfma_f32_16x16x32_bf16 v[18:21], v[194:197], v[218:221], v[18:21]
	v_mfma_f32_16x16x32_bf16 v[10:13], v[186:189], v[226:229], v[10:13]
	v_mfma_f32_16x16x32_bf16 v[2:5], v[194:197], v[226:229], v[2:5]
	v_mfma_f32_16x16x32_bf16 v[58:61], v[190:193], v[206:209], v[58:61]
	v_mfma_f32_16x16x32_bf16 v[50:53], v[198:201], v[206:209], v[50:53]
	v_mfma_f32_16x16x32_bf16 v[42:45], v[190:193], v[214:217], v[42:45]
	v_mfma_f32_16x16x32_bf16 v[34:37], v[198:201], v[214:217], v[34:37]
	v_mfma_f32_16x16x32_bf16 v[26:29], v[190:193], v[222:225], v[26:29]
	v_mfma_f32_16x16x32_bf16 v[18:21], v[198:201], v[222:225], v[18:21]
	v_mfma_f32_16x16x32_bf16 v[10:13], v[190:193], v[230:233], v[10:13]
	v_mfma_f32_16x16x32_bf16 v[2:5], v[198:201], v[230:233], v[2:5]
	s_setprio 0
	s_barrier
	s_add_i32 s65, s65, 2
	s_add_u32 s40, s40, 0x100
	s_addc_u32 s41, s41, 0
	s_add_u32 s63, s63, 0x100
	s_addc_u32 s64, s64, 0
	s_cmp_gt_u32 s65, 13
	s_cbranch_scc0 .LBB0_179
	s_waitcnt vmcnt(0)
	s_mov_b32 s99, 1
	s_and_b64 vcc, s[8:9], s[4:5]
	s_cbranch_vccz .LBB0_182
	s_barrier
.LBB0_182:
	s_waitcnt vmcnt(0)
	v_fmamk_f32 v186, v166, 0x3a800000, v161
	v_rsq_f32_e32 v189, v186
	v_lshl_or_b32 v202, s60, 7, v159
	v_lshlrev_b32_e32 v202, 1, v202
	v_mad_u32_u24 v194, v156, s59, v202
	v_mul_f32_e32 v188, 0xbfb8aa3b, v189
	v_fmamk_f32 v190, v165, 0x3a800000, v161
	v_rsq_f32_e32 v193, v190
	v_add_u32_e32 v195, 0x16000, v194
	v_add_u32_e32 v196, 0x2c000, v194
	v_add_u32_e32 v197, 0x42000, v194
	v_add_u32_e32 v198, 0xb0000, v194
	v_add_u32_e32 v199, 0xc6000, v194
	v_add_u32_e32 v200, 0xdc000, v194
	v_add_u32_e32 v201, 0xf2000, v194
	v_mul_f32_e32 v192, 0xbfb8aa3b, v193
	v_pk_mul_f32 v[122:123], v[126:127], v[122:123]
	v_pk_mul_f32 v[124:125], v[128:129], v[124:125]
	v_pk_mul_f32 v[114:115], v[118:119], v[114:115]
	v_pk_mul_f32 v[116:117], v[120:121], v[116:117]
	v_pk_mul_f32 v[126:127], v[126:127], v[188:189] op_sel_hi:[1,0]
	v_pk_mul_f32 v[128:129], v[128:129], v[188:189] op_sel_hi:[1,0]
	v_pk_mul_f32 v[118:119], v[118:119], v[188:189] op_sel_hi:[1,0]
	v_pk_mul_f32 v[120:121], v[120:121], v[188:189] op_sel_hi:[1,0]
	v_exp_f32_e32 v126, v126
	v_exp_f32_e32 v127, v127
	v_exp_f32_e32 v128, v128
	v_exp_f32_e32 v129, v129
	v_exp_f32_e32 v118, v118
	v_exp_f32_e32 v119, v119
	v_exp_f32_e32 v120, v120
	v_exp_f32_e32 v121, v121
	v_pk_fma_f32 v[126:127], v[126:127], v[186:187], v[186:187] op_sel_hi:[1,0,0]
	v_pk_fma_f32 v[128:129], v[128:129], v[186:187], v[186:187] op_sel_hi:[1,0,0]
	v_pk_fma_f32 v[118:119], v[118:119], v[186:187], v[186:187] op_sel_hi:[1,0,0]
	v_pk_fma_f32 v[120:121], v[120:121], v[186:187], v[186:187] op_sel_hi:[1,0,0]
	v_rcp_f32_e32 v126, v126
	v_rcp_f32_e32 v127, v127
	v_rcp_f32_e32 v128, v128
	v_rcp_f32_e32 v129, v129
	v_rcp_f32_e32 v118, v118
	v_rcp_f32_e32 v119, v119
	v_rcp_f32_e32 v120, v120
	v_rcp_f32_e32 v121, v121
	v_fmamk_f32 v186, v164, 0x3a800000, v161
	v_rsq_f32_e32 v189, v186
	v_pk_mul_f32 v[122:123], v[126:127], v[122:123]
; DI float fast_exp2(float x) { return __builtin_amdgcn_exp2f(x); }
; DI float fast_rcp(float x) { return __builtin_amdgcn_rcpf(x); }
;     DI void operator()(Acc& acc, const pg8::Unit& u, int wr, int wc, int fr, int fq, const Pre& pr) const {
;         const int col = u.pn * 128 + wc * 32 + fq * 8;
; #pragma unroll
;         for (int ai = 0; ai < 2; ++ai)
; #pragma unroll
;             for (int m = 0; m < 4; ++m) {
;                 const int row = u.pm * 256 + ai * 128 + wr * 64 + m * 16 + fr;
;                 const float msq = msq_of(pr.v[ai * 4 + m]), nrl = -1.4426950408889634f * __builtin_amdgcn_rsqf(msq);
;                 f32x4 h[2];
; #pragma unroll
;                 for (int n = 0; n < 2; ++n)
; #pragma unroll
;                     for (int i = 0; i < 4; ++i) { const float ga = acc[ai][0][m][n][i], ua = acc[ai][1][m][n][i];
;                         const float e = fast_exp2(ga * nrl); h[n][i] = (ga * ua) * fast_rcp(__builtin_fmaf(e, msq, msq)); }
;                 store8(H + (size_t)row * FF + col, h[0], h[1]);
;             }
	v_pk_mul_f32 v[124:125], v[128:129], v[124:125]
	v_pk_mul_f32 v[114:115], v[118:119], v[114:115]
	v_pk_mul_f32 v[116:117], v[120:121], v[116:117]
	v_cvt_pk_bf16_f32 v126, v122, v123
	v_cvt_pk_bf16_f32 v127, v124, v125
	v_cvt_pk_bf16_f32 v128, v114, v115
	v_cvt_pk_bf16_f32 v129, v116, v117
	v_mul_f32_e32 v188, 0xbfb8aa3b, v189
	v_pk_mul_f32 v[106:107], v[110:111], v[106:107]
	v_pk_mul_f32 v[108:109], v[112:113], v[108:109]
	v_pk_mul_f32 v[98:99], v[102:103], v[98:99]
	v_pk_mul_f32 v[100:101], v[104:105], v[100:101]
	v_pk_mul_f32 v[110:111], v[110:111], v[192:193] op_sel_hi:[1,0]
	v_pk_mul_f32 v[112:113], v[112:113], v[192:193] op_sel_hi:[1,0]
	v_pk_mul_f32 v[102:103], v[102:103], v[192:193] op_sel_hi:[1,0]
	v_pk_mul_f32 v[104:105], v[104:105], v[192:193] op_sel_hi:[1,0]
	v_exp_f32_e32 v110, v110
	v_exp_f32_e32 v111, v111
	v_exp_f32_e32 v112, v112
	v_exp_f32_e32 v113, v113
	v_exp_f32_e32 v102, v102
	v_exp_f32_e32 v103, v103
	v_exp_f32_e32 v104, v104
	v_exp_f32_e32 v105, v105
	global_store_dwordx4 v194, v[126:129], s[10:11]
	v_pk_fma_f32 v[110:111], v[110:111], v[190:191], v[190:191] op_sel_hi:[1,0,0]
	v_pk_fma_f32 v[112:113], v[112:113], v[190:191], v[190:191] op_sel_hi:[1,0,0]
	v_pk_fma_f32 v[102:103], v[102:103], v[190:191], v[190:191] op_sel_hi:[1,0,0]
	v_pk_fma_f32 v[104:105], v[104:105], v[190:191], v[190:191] op_sel_hi:[1,0,0]
	v_rcp_f32_e32 v110, v110
	v_rcp_f32_e32 v111, v111
	v_rcp_f32_e32 v112, v112
	v_rcp_f32_e32 v113, v113
	v_rcp_f32_e32 v102, v102
	v_rcp_f32_e32 v103, v103
	v_rcp_f32_e32 v104, v104
	v_rcp_f32_e32 v105, v105
	v_fmamk_f32 v190, v157, 0x3a800000, v161
	v_rsq_f32_e32 v193, v190
	v_pk_mul_f32 v[106:107], v[110:111], v[106:107]
	v_pk_mul_f32 v[108:109], v[112:113], v[108:109]
	v_pk_mul_f32 v[98:99], v[102:103], v[98:99]
	v_pk_mul_f32 v[100:101], v[104:105], v[100:101]
	v_cvt_pk_bf16_f32 v110, v106, v107
	v_cvt_pk_bf16_f32 v111, v108, v109
	v_cvt_pk_bf16_f32 v112, v98, v99
	v_cvt_pk_bf16_f32 v113, v100, v101
	v_mul_f32_e32 v192, 0xbfb8aa3b, v193
	v_pk_mul_f32 v[90:91], v[94:95], v[90:91]
	v_pk_mul_f32 v[92:93], v[96:97], v[92:93]
	v_pk_mul_f32 v[82:83], v[86:87], v[82:83]
	v_pk_mul_f32 v[84:85], v[88:89], v[84:85]
	v_pk_mul_f32 v[94:95], v[94:95], v[188:189] op_sel_hi:[1,0]
	v_pk_mul_f32 v[96:97], v[96:97], v[188:189] op_sel_hi:[1,0]
	v_pk_mul_f32 v[86:87], v[86:87], v[188:189] op_sel_hi:[1,0]
	v_pk_mul_f32 v[88:89], v[88:89], v[188:189] op_sel_hi:[1,0]
	v_exp_f32_e32 v94, v94
	v_exp_f32_e32 v95, v95
	v_exp_f32_e32 v96, v96
	v_exp_f32_e32 v97, v97
	v_exp_f32_e32 v86, v86
	v_exp_f32_e32 v87, v87
	v_exp_f32_e32 v88, v88
	v_exp_f32_e32 v89, v89
	global_store_dwordx4 v195, v[110:113], s[10:11]
	v_pk_fma_f32 v[94:95], v[94:95], v[186:187], v[186:187] op_sel_hi:[1,0,0]
	v_pk_fma_f32 v[96:97], v[96:97], v[186:187], v[186:187] op_sel_hi:[1,0,0]
	v_pk_fma_f32 v[86:87], v[86:87], v[186:187], v[186:187] op_sel_hi:[1,0,0]
	v_pk_fma_f32 v[88:89], v[88:89], v[186:187], v[186:187] op_sel_hi:[1,0,0]
	v_rcp_f32_e32 v94, v94
	v_rcp_f32_e32 v95, v95
	v_rcp_f32_e32 v96, v96
	v_rcp_f32_e32 v97, v97
	v_rcp_f32_e32 v86, v86
	v_rcp_f32_e32 v87, v87
	v_rcp_f32_e32 v88, v88
	v_rcp_f32_e32 v89, v89
	v_fmamk_f32 v186, v155, 0x3a800000, v161
	v_rsq_f32_e32 v189, v186
	v_pk_mul_f32 v[90:91], v[94:95], v[90:91]
	v_pk_mul_f32 v[92:93], v[96:97], v[92:93]
	v_pk_mul_f32 v[82:83], v[86:87], v[82:83]
	v_pk_mul_f32 v[84:85], v[88:89], v[84:85]
	v_cvt_pk_bf16_f32 v94, v90, v91
	v_cvt_pk_bf16_f32 v95, v92, v93
	v_cvt_pk_bf16_f32 v96, v82, v83
	v_cvt_pk_bf16_f32 v97, v84, v85
	v_mul_f32_e32 v188, 0xbfb8aa3b, v189
	v_pk_mul_f32 v[74:75], v[78:79], v[74:75]
	v_pk_mul_f32 v[76:77], v[80:81], v[76:77]
	v_pk_mul_f32 v[66:67], v[70:71], v[66:67]
	v_pk_mul_f32 v[68:69], v[72:73], v[68:69]
	v_pk_mul_f32 v[78:79], v[78:79], v[192:193] op_sel_hi:[1,0]
	v_pk_mul_f32 v[80:81], v[80:81], v[192:193] op_sel_hi:[1,0]
	v_pk_mul_f32 v[70:71], v[70:71], v[192:193] op_sel_hi:[1,0]
	v_pk_mul_f32 v[72:73], v[72:73], v[192:193] op_sel_hi:[1,0]
	v_exp_f32_e32 v78, v78
	v_exp_f32_e32 v79, v79
	v_exp_f32_e32 v80, v80
	v_exp_f32_e32 v81, v81
	v_exp_f32_e32 v70, v70
	v_exp_f32_e32 v71, v71
	v_exp_f32_e32 v72, v72
	v_exp_f32_e32 v73, v73
	global_store_dwordx4 v196, v[94:97], s[10:11]
	v_pk_fma_f32 v[78:79], v[78:79], v[190:191], v[190:191] op_sel_hi:[1,0,0]
	v_pk_fma_f32 v[80:81], v[80:81], v[190:191], v[190:191] op_sel_hi:[1,0,0]
	v_pk_fma_f32 v[70:71], v[70:71], v[190:191], v[190:191] op_sel_hi:[1,0,0]
	v_pk_fma_f32 v[72:73], v[72:73], v[190:191], v[190:191] op_sel_hi:[1,0,0]
	v_rcp_f32_e32 v78, v78
	v_rcp_f32_e32 v79, v79
	v_rcp_f32_e32 v80, v80
	v_rcp_f32_e32 v81, v81
	v_rcp_f32_e32 v70, v70
	v_rcp_f32_e32 v71, v71
	v_rcp_f32_e32 v72, v72
	v_rcp_f32_e32 v73, v73
	v_fmamk_f32 v190, v153, 0x3a800000, v161
	v_rsq_f32_e32 v193, v190
	v_pk_mul_f32 v[74:75], v[78:79], v[74:75]
	v_pk_mul_f32 v[76:77], v[80:81], v[76:77]
	v_pk_mul_f32 v[66:67], v[70:71], v[66:67]
	v_pk_mul_f32 v[68:69], v[72:73], v[68:69]
	v_cvt_pk_bf16_f32 v78, v74, v75
	v_cvt_pk_bf16_f32 v79, v76, v77
	v_cvt_pk_bf16_f32 v80, v66, v67
	v_cvt_pk_bf16_f32 v81, v68, v69
	v_mul_f32_e32 v192, 0xbfb8aa3b, v193
	v_pk_mul_f32 v[58:59], v[62:63], v[58:59]
	v_pk_mul_f32 v[60:61], v[64:65], v[60:61]
	v_pk_mul_f32 v[50:51], v[54:55], v[50:51]
	v_pk_mul_f32 v[52:53], v[56:57], v[52:53]
	v_pk_mul_f32 v[62:63], v[62:63], v[188:189] op_sel_hi:[1,0]
	v_pk_mul_f32 v[64:65], v[64:65], v[188:189] op_sel_hi:[1,0]
	v_pk_mul_f32 v[54:55], v[54:55], v[188:189] op_sel_hi:[1,0]
	v_pk_mul_f32 v[56:57], v[56:57], v[188:189] op_sel_hi:[1,0]
	v_exp_f32_e32 v62, v62
	v_exp_f32_e32 v63, v63
	v_exp_f32_e32 v64, v64
	v_exp_f32_e32 v65, v65
; DI float fast_exp2(float x) { return __builtin_amdgcn_exp2f(x); }
; DI float fast_rcp(float x) { return __builtin_amdgcn_rcpf(x); }
; #define PG8_BAR __builtin_amdgcn_s_barrier()
;     DI void pre(Pre& pr, const pg8::Unit& u, int wr, int fr) const { load_rows(pr, ssq, u, wr, fr); }
;     DI void pre(Pre& pr, const pg8::Unit& u, int wr, int fr) const { load_rows(pr, ssq, u, wr, fr); }
; template <class Epi, class Sched>
; DI void gemm_phase(LAS unsigned char* lds, const Gemm g, const Sched& S, const Epi& E) {
;     ...
;         if (wr == 0) PG8_BAR;
;         E(acc, cur, wr, wc, fr, fq, pre);
;         if (!has_next) break;
;         if (!(Epi::CHAIN && cur.src == 0)) {
; #pragma unroll
;             for (int a = 0; a < 2; ++a)
; #pragma unroll
;                 for (int b = 0; b < 2; ++b)
; #pragma unroll
;                     for (int m = 0; m < 4; ++m)
; #pragma unroll
;                         for (int n = 0; n < 2; ++n) acc[a][b][m][n] = (f32x4){0.f, 0.f, 0.f, 0.f};
;         }
;         cur = nxt; cA = nA; cB = nB; ++ui;
;         if (wr == 1) PG8_BAR;
;     DI void operator()(Acc& acc, const pg8::Unit& u, int wr, int wc, int fr, int fq, const Pre& pr) const {
;         const int col = u.pn * 128 + wc * 32 + fq * 8;
; #pragma unroll
;         for (int ai = 0; ai < 2; ++ai)
; #pragma unroll
;             for (int m = 0; m < 4; ++m) {
;                 const int row = u.pm * 256 + ai * 128 + wr * 64 + m * 16 + fr;
;                 const float msq = msq_of(pr.v[ai * 4 + m]), nrl = -1.4426950408889634f * __builtin_amdgcn_rsqf(msq);
;                 f32x4 h[2];
; #pragma unroll
;                 for (int n = 0; n < 2; ++n)
; #pragma unroll
;                     for (int i = 0; i < 4; ++i) { const float ga = acc[ai][0][m][n][i], ua = acc[ai][1][m][n][i];
;                         const float e = fast_exp2(ga * nrl); h[n][i] = (ga * ua) * fast_rcp(__builtin_fmaf(e, msq, msq)); }
;                 store8(H + (size_t)row * FF + col, h[0], h[1]);
;             }
	v_exp_f32_e32 v54, v54
	v_exp_f32_e32 v55, v55
	v_exp_f32_e32 v56, v56
	v_exp_f32_e32 v57, v57
	global_store_dwordx4 v197, v[78:81], s[10:11]
	v_pk_fma_f32 v[62:63], v[62:63], v[186:187], v[186:187] op_sel_hi:[1,0,0]
	v_pk_fma_f32 v[64:65], v[64:65], v[186:187], v[186:187] op_sel_hi:[1,0,0]
	v_pk_fma_f32 v[54:55], v[54:55], v[186:187], v[186:187] op_sel_hi:[1,0,0]
	v_pk_fma_f32 v[56:57], v[56:57], v[186:187], v[186:187] op_sel_hi:[1,0,0]
	v_rcp_f32_e32 v62, v62
	v_rcp_f32_e32 v63, v63
	v_rcp_f32_e32 v64, v64
	v_rcp_f32_e32 v65, v65
	v_rcp_f32_e32 v54, v54
	v_rcp_f32_e32 v55, v55
	v_rcp_f32_e32 v56, v56
	v_rcp_f32_e32 v57, v57
	v_fmamk_f32 v186, v151, 0x3a800000, v161
	v_rsq_f32_e32 v189, v186
	v_pk_mul_f32 v[58:59], v[62:63], v[58:59]
	v_pk_mul_f32 v[60:61], v[64:65], v[60:61]
	v_pk_mul_f32 v[50:51], v[54:55], v[50:51]
	v_pk_mul_f32 v[52:53], v[56:57], v[52:53]
	v_cvt_pk_bf16_f32 v62, v58, v59
	v_cvt_pk_bf16_f32 v63, v60, v61
	v_cvt_pk_bf16_f32 v64, v50, v51
	v_cvt_pk_bf16_f32 v65, v52, v53
	v_mul_f32_e32 v188, 0xbfb8aa3b, v189
	v_pk_mul_f32 v[42:43], v[46:47], v[42:43]
	v_pk_mul_f32 v[44:45], v[48:49], v[44:45]
	v_pk_mul_f32 v[34:35], v[38:39], v[34:35]
	v_pk_mul_f32 v[36:37], v[40:41], v[36:37]
	v_pk_mul_f32 v[46:47], v[46:47], v[192:193] op_sel_hi:[1,0]
	v_pk_mul_f32 v[48:49], v[48:49], v[192:193] op_sel_hi:[1,0]
	v_pk_mul_f32 v[38:39], v[38:39], v[192:193] op_sel_hi:[1,0]
	v_pk_mul_f32 v[40:41], v[40:41], v[192:193] op_sel_hi:[1,0]
	v_exp_f32_e32 v46, v46
	v_exp_f32_e32 v47, v47
	v_exp_f32_e32 v48, v48
	v_exp_f32_e32 v49, v49
	v_exp_f32_e32 v38, v38
	v_exp_f32_e32 v39, v39
	v_exp_f32_e32 v40, v40
	v_exp_f32_e32 v41, v41
	global_store_dwordx4 v198, v[62:65], s[10:11]
	v_pk_fma_f32 v[46:47], v[46:47], v[190:191], v[190:191] op_sel_hi:[1,0,0]
	v_pk_fma_f32 v[48:49], v[48:49], v[190:191], v[190:191] op_sel_hi:[1,0,0]
	v_pk_fma_f32 v[38:39], v[38:39], v[190:191], v[190:191] op_sel_hi:[1,0,0]
	v_pk_fma_f32 v[40:41], v[40:41], v[190:191], v[190:191] op_sel_hi:[1,0,0]
	v_rcp_f32_e32 v46, v46
	v_rcp_f32_e32 v47, v47
	v_rcp_f32_e32 v48, v48
	v_rcp_f32_e32 v49, v49
	v_rcp_f32_e32 v38, v38
	v_rcp_f32_e32 v39, v39
	v_rcp_f32_e32 v40, v40
	v_rcp_f32_e32 v41, v41
	v_fmamk_f32 v190, v149, 0x3a800000, v161
	v_rsq_f32_e32 v193, v190
	v_pk_mul_f32 v[42:43], v[46:47], v[42:43]
	v_pk_mul_f32 v[44:45], v[48:49], v[44:45]
	v_pk_mul_f32 v[34:35], v[38:39], v[34:35]
	v_pk_mul_f32 v[36:37], v[40:41], v[36:37]
	v_cvt_pk_bf16_f32 v46, v42, v43
	v_cvt_pk_bf16_f32 v47, v44, v45
	v_cvt_pk_bf16_f32 v48, v34, v35
	v_cvt_pk_bf16_f32 v49, v36, v37
	v_mul_f32_e32 v192, 0xbfb8aa3b, v193
	v_pk_mul_f32 v[26:27], v[30:31], v[26:27]
	v_pk_mul_f32 v[28:29], v[32:33], v[28:29]
	v_pk_mul_f32 v[18:19], v[22:23], v[18:19]
	v_pk_mul_f32 v[20:21], v[24:25], v[20:21]
	v_pk_mul_f32 v[30:31], v[30:31], v[188:189] op_sel_hi:[1,0]
	v_pk_mul_f32 v[32:33], v[32:33], v[188:189] op_sel_hi:[1,0]
	v_pk_mul_f32 v[22:23], v[22:23], v[188:189] op_sel_hi:[1,0]
	v_pk_mul_f32 v[24:25], v[24:25], v[188:189] op_sel_hi:[1,0]
	v_exp_f32_e32 v30, v30
	v_exp_f32_e32 v31, v31
	v_exp_f32_e32 v32, v32
	v_exp_f32_e32 v33, v33
	v_exp_f32_e32 v22, v22
	v_exp_f32_e32 v23, v23
	v_exp_f32_e32 v24, v24
	v_exp_f32_e32 v25, v25
	global_store_dwordx4 v199, v[46:49], s[10:11]
	v_pk_fma_f32 v[30:31], v[30:31], v[186:187], v[186:187] op_sel_hi:[1,0,0]
	v_pk_fma_f32 v[32:33], v[32:33], v[186:187], v[186:187] op_sel_hi:[1,0,0]
	v_pk_fma_f32 v[22:23], v[22:23], v[186:187], v[186:187] op_sel_hi:[1,0,0]
	v_pk_fma_f32 v[24:25], v[24:25], v[186:187], v[186:187] op_sel_hi:[1,0,0]
	v_rcp_f32_e32 v30, v30
	v_rcp_f32_e32 v31, v31
	v_rcp_f32_e32 v32, v32
	v_rcp_f32_e32 v33, v33
	v_rcp_f32_e32 v22, v22
	v_rcp_f32_e32 v23, v23
	v_rcp_f32_e32 v24, v24
	v_rcp_f32_e32 v25, v25
	v_pk_mul_f32 v[26:27], v[30:31], v[26:27]
	v_pk_mul_f32 v[28:29], v[32:33], v[28:29]
	v_pk_mul_f32 v[18:19], v[22:23], v[18:19]
	v_pk_mul_f32 v[20:21], v[24:25], v[20:21]
	v_cvt_pk_bf16_f32 v30, v26, v27
	v_cvt_pk_bf16_f32 v31, v28, v29
	v_cvt_pk_bf16_f32 v32, v18, v19
	v_cvt_pk_bf16_f32 v33, v20, v21
	v_pk_mul_f32 v[10:11], v[14:15], v[10:11]
	v_pk_mul_f32 v[12:13], v[16:17], v[12:13]
	v_pk_mul_f32 v[2:3], v[6:7], v[2:3]
	v_pk_mul_f32 v[4:5], v[8:9], v[4:5]
	v_pk_mul_f32 v[14:15], v[14:15], v[192:193] op_sel_hi:[1,0]
	v_pk_mul_f32 v[16:17], v[16:17], v[192:193] op_sel_hi:[1,0]
	v_pk_mul_f32 v[6:7], v[6:7], v[192:193] op_sel_hi:[1,0]
	v_pk_mul_f32 v[8:9], v[8:9], v[192:193] op_sel_hi:[1,0]
	v_exp_f32_e32 v14, v14
	v_exp_f32_e32 v15, v15
	v_exp_f32_e32 v16, v16
	v_exp_f32_e32 v17, v17
	v_exp_f32_e32 v6, v6
	v_exp_f32_e32 v7, v7
	v_exp_f32_e32 v8, v8
	v_exp_f32_e32 v9, v9
	global_store_dwordx4 v200, v[30:33], s[10:11]
	v_pk_fma_f32 v[14:15], v[14:15], v[190:191], v[190:191] op_sel_hi:[1,0,0]
	v_pk_fma_f32 v[16:17], v[16:17], v[190:191], v[190:191] op_sel_hi:[1,0,0]
	v_pk_fma_f32 v[6:7], v[6:7], v[190:191], v[190:191] op_sel_hi:[1,0,0]
	v_pk_fma_f32 v[8:9], v[8:9], v[190:191], v[190:191] op_sel_hi:[1,0,0]
	v_rcp_f32_e32 v14, v14
	v_rcp_f32_e32 v15, v15
	v_rcp_f32_e32 v16, v16
	v_rcp_f32_e32 v17, v17
	v_rcp_f32_e32 v6, v6
	v_rcp_f32_e32 v7, v7
	v_rcp_f32_e32 v8, v8
	v_rcp_f32_e32 v9, v9
	v_pk_mul_f32 v[10:11], v[14:15], v[10:11]
	v_pk_mul_f32 v[12:13], v[16:17], v[12:13]
	v_pk_mul_f32 v[2:3], v[6:7], v[2:3]
	v_pk_mul_f32 v[4:5], v[8:9], v[4:5]
	v_cvt_pk_bf16_f32 v14, v10, v11
	v_cvt_pk_bf16_f32 v15, v12, v13
	v_cvt_pk_bf16_f32 v16, v2, v3
	v_cvt_pk_bf16_f32 v17, v4, v5
	s_and_b64 vcc, exec, s[18:19]
	s_cbranch_vccz .Lgu1_noalign
	s_barrier
.Lgu1_noalign:
	s_andn2_b64 vcc, exec, s[4:5]
	s_mov_b64 s[4:5], -1
	global_store_dwordx4 v201, v[14:17], s[10:11]
	s_cbranch_vccnz .LBB0_175
	s_branch .LBB0_174

; #define PG8_STAGE(bufoff, gbase, voff) do { _Pragma("unroll") for (int _i = 0; _i < 2; ++_i) \
;         __builtin_amdgcn_global_load_lds((const unsigned*)((const char*)(gbase) + (voff)[_i]), (LAS unsigned*)(lds + (bufoff) + ldsw + _i * 8192), 16, 0, 0); } while (0)
; #define PG8_LDA(dst, b, h) do { _Pragma("unroll") for (int m = 0; m < 4; ++m) _Pragma("unroll") for (int k = 0; k < 2; ++k) dst[m][k] = *(const LAS bf16x8*)(lds + PG8_SA(b, h) + aoff + m * 2048 + k * 1024); } while (0)
; #define PG8_LDB(dst, b, h) do { _Pragma("unroll") for (int n = 0; n < 2; ++n) _Pragma("unroll") for (int k = 0; k < 2; ++k) dst[n][k] = *(const LAS bf16x8*)(lds + PG8_SB(b, h) + boff + n * 2048 + k * 1024); } while (0)
; #define PG8_MMA(ai, bj, At, Bt) do { __builtin_amdgcn_s_setprio(1); _Pragma("unroll") for (int m = 0; m < 4; ++m) _Pragma("unroll") for (int n = 0; n < 2; ++n) _Pragma("unroll") for (int k = 0; k < 2; ++k) \
;         acc[ai][bj][m][n] = __builtin_amdgcn_mfma_f32_16x16x32_bf16(Bt[n][k], At[m][k], acc[ai][bj][m][n], 0, 0, 0); __builtin_amdgcn_s_setprio(0); } while (0)
; #define PG8_WAIT_V(n) asm volatile("s_waitcnt vmcnt(" #n ")" ::: "memory")
; #define PG8_WAIT_L(n) asm volatile("s_waitcnt lgkmcnt(" #n ")" ::: "memory")
; #define PG8_BAR __builtin_amdgcn_s_barrier()
; #define PG8_SCHED __builtin_amdgcn_sched_barrier(0)
; template <class Epi, class Sched>
; DI void gemm_phase(LAS unsigned char* lds, const Gemm g, const Sched& S, const Epi& E) {
;     ...
;         for (int t = 0; t < nt; t += 2) {
;             const bool last = (t == nt - 2);
;             const char* a1 = cA + (size_t)(t + 1) * kstep;
;             const char* a2 = last ? nA : cA + (size_t)(t + 2) * kstep; const char* b2 = last ? nB : cB + (size_t)(t + 2) * kstep;
;             const char* a3 = a2 + kstep; const char* b3 = b2 + kstep;
;             PG8_LDB(B0, 0, 0); PG8_LDB(B1, 0, 1); PG8_SCHED; PG8_LDA(At, 0, 0); PG8_STAGE(PG8_SA(1, 1), a1 + hstepA, voffA);
;             PG8_WAIT_V(8); PG8_WAIT_L(0); PG8_BAR; PG8_MMA(0, 0, At, B0); PG8_MMA(0, 1, At, B1); PG8_BAR; PG8_SCHED;
;             PG8_LDA(At, 0, 1); PG8_STAGE(PG8_SB(0, 0), b2, voffB); PG8_STAGE(PG8_SB(0, 1), b2 + hstepB, voffB); PG8_STAGE(PG8_SA(0, 0), a2, voffA);
;             PG8_WAIT_V(8); PG8_WAIT_L(0); PG8_BAR; PG8_MMA(1, 0, At, B0); PG8_MMA(1, 1, At, B1); PG8_BAR; PG8_SCHED;
.LBB0_1234:
	ds_read_b128 v[166:169], v160
	ds_read_b128 v[170:173], v160 offset:1024
	ds_read_b128 v[174:177], v160 offset:2048
	ds_read_b128 v[178:181], v160 offset:3072
	ds_read_b128 v[186:189], v161
	ds_read_b128 v[190:193], v161 offset:1024
	ds_read_b128 v[194:197], v161 offset:2048
	ds_read_b128 v[198:201], v161 offset:3072
	s_add_u32 s42, s40, 0xfffc0080
	s_addc_u32 s43, s41, -1
	s_cmp_eq_u32 s65, 12
	s_cselect_b32 s45, s35, s43
	s_cselect_b32 s44, s61, s42
	s_cselect_b32 s43, s21, s64
	s_cselect_b32 s42, s62, s63
	v_lshl_add_u64 v[182:183], s[40:41], 0, v[138:139]
	s_add_i32 m0, s49, 0xc000
	ds_read_b128 v[202:205], v158
	ds_read_b128 v[206:209], v158 offset:1024
	ds_read_b128 v[210:213], v158 offset:2048
	ds_read_b128 v[214:217], v158 offset:3072
	ds_read_b128 v[218:221], v158 offset:4096
	ds_read_b128 v[222:225], v158 offset:5120
	ds_read_b128 v[226:229], v158 offset:6144
	ds_read_b128 v[230:233], v158 offset:7168
	global_load_lds_dwordx4 v[182:183], off
	v_lshl_add_u64 v[182:183], s[40:41], 0, v[140:141]
	s_add_i32 m0, s49, 0xe000
	s_nop 0
	global_load_lds_dwordx4 v[182:183], off
	s_waitcnt vmcnt(8)
	s_waitcnt lgkmcnt(0)
	s_barrier
	s_setprio 1
	v_mfma_f32_16x16x32_bf16 v[126:129], v[166:169], v[202:205], v[126:129]
	v_mfma_f32_16x16x32_bf16 v[118:121], v[174:177], v[202:205], v[118:121]
	v_mfma_f32_16x16x32_bf16 v[110:113], v[166:169], v[210:213], v[110:113]
	v_mfma_f32_16x16x32_bf16 v[102:105], v[174:177], v[210:213], v[102:105]
	v_mfma_f32_16x16x32_bf16 v[94:97], v[166:169], v[218:221], v[94:97]
	v_mfma_f32_16x16x32_bf16 v[86:89], v[174:177], v[218:221], v[86:89]
	v_mfma_f32_16x16x32_bf16 v[78:81], v[166:169], v[226:229], v[78:81]
	v_mfma_f32_16x16x32_bf16 v[70:73], v[174:177], v[226:229], v[70:73]
	v_mfma_f32_16x16x32_bf16 v[126:129], v[170:173], v[206:209], v[126:129]
	v_mfma_f32_16x16x32_bf16 v[118:121], v[178:181], v[206:209], v[118:121]
	v_mfma_f32_16x16x32_bf16 v[110:113], v[170:173], v[214:217], v[110:113]
	v_mfma_f32_16x16x32_bf16 v[102:105], v[178:181], v[214:217], v[102:105]
	v_mfma_f32_16x16x32_bf16 v[94:97], v[170:173], v[222:225], v[94:97]
	v_mfma_f32_16x16x32_bf16 v[86:89], v[178:181], v[222:225], v[86:89]
	v_mfma_f32_16x16x32_bf16 v[78:81], v[170:173], v[230:233], v[78:81]
	v_mfma_f32_16x16x32_bf16 v[70:73], v[178:181], v[230:233], v[70:73]
	v_mfma_f32_16x16x32_bf16 v[122:125], v[186:189], v[202:205], v[122:125]
	v_mfma_f32_16x16x32_bf16 v[114:117], v[194:197], v[202:205], v[114:117]
	v_mfma_f32_16x16x32_bf16 v[106:109], v[186:189], v[210:213], v[106:109]
	v_mfma_f32_16x16x32_bf16 v[98:101], v[194:197], v[210:213], v[98:101]
	v_mfma_f32_16x16x32_bf16 v[90:93], v[186:189], v[218:221], v[90:93]
	v_mfma_f32_16x16x32_bf16 v[82:85], v[194:197], v[218:221], v[82:85]
	v_mfma_f32_16x16x32_bf16 v[74:77], v[186:189], v[226:229], v[74:77]
	v_mfma_f32_16x16x32_bf16 v[66:69], v[194:197], v[226:229], v[66:69]
	v_mfma_f32_16x16x32_bf16 v[122:125], v[190:193], v[206:209], v[122:125]
	v_mfma_f32_16x16x32_bf16 v[114:117], v[198:201], v[206:209], v[114:117]
	v_mfma_f32_16x16x32_bf16 v[106:109], v[190:193], v[214:217], v[106:109]
	v_mfma_f32_16x16x32_bf16 v[98:101], v[198:201], v[214:217], v[98:101]
	v_mfma_f32_16x16x32_bf16 v[90:93], v[190:193], v[222:225], v[90:93]
	v_mfma_f32_16x16x32_bf16 v[82:85], v[198:201], v[222:225], v[82:85]
	v_mfma_f32_16x16x32_bf16 v[74:77], v[190:193], v[230:233], v[74:77]
	v_mfma_f32_16x16x32_bf16 v[66:69], v[198:201], v[230:233], v[66:69]
	s_setprio 0
	s_barrier
	s_add_i32 s66, s57, s46
	v_lshl_add_u64 v[182:183], s[42:43], 0, v[134:135]
	s_mov_b32 m0, s66
	ds_read_b128 v[202:205], v158 offset:16384
	ds_read_b128 v[206:209], v158 offset:17408
	ds_read_b128 v[210:213], v158 offset:18432
	ds_read_b128 v[214:217], v158 offset:19456
	ds_read_b128 v[218:221], v158 offset:20480
	ds_read_b128 v[222:225], v158 offset:21504
	ds_read_b128 v[226:229], v158 offset:22528
	ds_read_b128 v[230:233], v158 offset:23552
	global_load_lds_dwordx4 v[182:183], off
	s_add_i32 m0, s66, 0x2000
	s_add_u32 s66, s42, 0x40000
	v_lshl_add_u64 v[234:235], s[42:43], 0, v[130:131]
	s_addc_u32 s67, s43, 0
	s_add_i32 s68, s58, s46
	global_load_lds_dwordx4 v[234:235], off
	v_lshl_add_u64 v[236:237], s[66:67], 0, v[134:135]
	s_mov_b32 m0, s68
	v_lshl_add_u64 v[238:239], s[44:45], 0, v[132:133]
	global_load_lds_dwordx4 v[236:237], off
	v_lshl_add_u64 v[236:237], s[66:67], 0, v[130:131]
	s_add_i32 m0, s68, 0x2000
	s_nop 0
	global_load_lds_dwordx4 v[236:237], off
	v_lshl_add_u64 v[236:237], s[44:45], 0, v[136:137]
	s_mov_b32 m0, s49
	s_nop 0
	global_load_lds_dwordx4 v[236:237], off
	s_mov_b32 m0, s50
	s_nop 0
	global_load_lds_dwordx4 v[238:239], off
	s_waitcnt vmcnt(8)
	s_waitcnt lgkmcnt(0)
	s_barrier
; #define PG8_STAGE(bufoff, gbase, voff) do { _Pragma("unroll") for (int _i = 0; _i < 2; ++_i) \
;         __builtin_amdgcn_global_load_lds((const unsigned*)((const char*)(gbase) + (voff)[_i]), (LAS unsigned*)(lds + (bufoff) + ldsw + _i * 8192), 16, 0, 0); } while (0)
; #define PG8_LDA(dst, b, h) do { _Pragma("unroll") for (int m = 0; m < 4; ++m) _Pragma("unroll") for (int k = 0; k < 2; ++k) dst[m][k] = *(const LAS bf16x8*)(lds + PG8_SA(b, h) + aoff + m * 2048 + k * 1024); } while (0)
; #define PG8_LDB(dst, b, h) do { _Pragma("unroll") for (int n = 0; n < 2; ++n) _Pragma("unroll") for (int k = 0; k < 2; ++k) dst[n][k] = *(const LAS bf16x8*)(lds + PG8_SB(b, h) + boff + n * 2048 + k * 1024); } while (0)
; #define PG8_MMA(ai, bj, At, Bt) do { __builtin_amdgcn_s_setprio(1); _Pragma("unroll") for (int m = 0; m < 4; ++m) _Pragma("unroll") for (int n = 0; n < 2; ++n) _Pragma("unroll") for (int k = 0; k < 2; ++k) \
;         acc[ai][bj][m][n] = __builtin_amdgcn_mfma_f32_16x16x32_bf16(Bt[n][k], At[m][k], acc[ai][bj][m][n], 0, 0, 0); __builtin_amdgcn_s_setprio(0); } while (0)
; #define PG8_WAIT_V(n) asm volatile("s_waitcnt vmcnt(" #n ")" ::: "memory")
; #define PG8_WAIT_L(n) asm volatile("s_waitcnt lgkmcnt(" #n ")" ::: "memory")
; #define PG8_BAR __builtin_amdgcn_s_barrier()
; #define PG8_SCHED __builtin_amdgcn_sched_barrier(0)
; template <class Epi, class Sched>
; DI void gemm_phase(LAS unsigned char* lds, const Gemm g, const Sched& S, const Epi& E) {
;     ...
;             PG8_WAIT_V(8); PG8_WAIT_L(0); PG8_BAR; PG8_MMA(1, 0, At, B0); PG8_MMA(1, 1, At, B1); PG8_BAR; PG8_SCHED;
;             PG8_LDB(B0, 1, 0); PG8_LDB(B1, 1, 1); PG8_SCHED; PG8_LDA(At, 1, 0); PG8_STAGE(PG8_SA(0, 1), a2 + hstepA, voffA);
;             PG8_WAIT_V(8); PG8_WAIT_L(0); PG8_BAR; PG8_MMA(0, 0, At, B0); PG8_MMA(0, 1, At, B1); PG8_BAR; PG8_SCHED;
	s_setprio 1
	v_mfma_f32_16x16x32_bf16 v[62:65], v[166:169], v[202:205], v[62:65]
	v_mfma_f32_16x16x32_bf16 v[54:57], v[174:177], v[202:205], v[54:57]
	v_mfma_f32_16x16x32_bf16 v[46:49], v[166:169], v[210:213], v[46:49]
	v_mfma_f32_16x16x32_bf16 v[38:41], v[174:177], v[210:213], v[38:41]
	v_mfma_f32_16x16x32_bf16 v[30:33], v[166:169], v[218:221], v[30:33]
	v_mfma_f32_16x16x32_bf16 v[22:25], v[174:177], v[218:221], v[22:25]
	v_mfma_f32_16x16x32_bf16 v[14:17], v[166:169], v[226:229], v[14:17]
	v_mfma_f32_16x16x32_bf16 v[6:9], v[174:177], v[226:229], v[6:9]
	v_mfma_f32_16x16x32_bf16 v[62:65], v[170:173], v[206:209], v[62:65]
	v_mfma_f32_16x16x32_bf16 v[54:57], v[178:181], v[206:209], v[54:57]
	v_mfma_f32_16x16x32_bf16 v[46:49], v[170:173], v[214:217], v[46:49]
	v_mfma_f32_16x16x32_bf16 v[38:41], v[178:181], v[214:217], v[38:41]
	v_mfma_f32_16x16x32_bf16 v[30:33], v[170:173], v[222:225], v[30:33]
	v_mfma_f32_16x16x32_bf16 v[22:25], v[178:181], v[222:225], v[22:25]
	v_mfma_f32_16x16x32_bf16 v[14:17], v[170:173], v[230:233], v[14:17]
	v_mfma_f32_16x16x32_bf16 v[6:9], v[178:181], v[230:233], v[6:9]
	v_mfma_f32_16x16x32_bf16 v[58:61], v[186:189], v[202:205], v[58:61]
	v_mfma_f32_16x16x32_bf16 v[50:53], v[194:197], v[202:205], v[50:53]
	v_mfma_f32_16x16x32_bf16 v[42:45], v[186:189], v[210:213], v[42:45]
	v_mfma_f32_16x16x32_bf16 v[34:37], v[194:197], v[210:213], v[34:37]
	v_mfma_f32_16x16x32_bf16 v[26:29], v[186:189], v[218:221], v[26:29]
	v_mfma_f32_16x16x32_bf16 v[18:21], v[194:197], v[218:221], v[18:21]
	v_mfma_f32_16x16x32_bf16 v[10:13], v[186:189], v[226:229], v[10:13]
	v_mfma_f32_16x16x32_bf16 v[2:5], v[194:197], v[226:229], v[2:5]
	v_mfma_f32_16x16x32_bf16 v[58:61], v[190:193], v[206:209], v[58:61]
	v_mfma_f32_16x16x32_bf16 v[50:53], v[198:201], v[206:209], v[50:53]
	v_mfma_f32_16x16x32_bf16 v[42:45], v[190:193], v[214:217], v[42:45]
	v_mfma_f32_16x16x32_bf16 v[34:37], v[198:201], v[214:217], v[34:37]
	v_mfma_f32_16x16x32_bf16 v[26:29], v[190:193], v[222:225], v[26:29]
	v_mfma_f32_16x16x32_bf16 v[18:21], v[198:201], v[222:225], v[18:21]
	v_mfma_f32_16x16x32_bf16 v[10:13], v[190:193], v[230:233], v[10:13]
	v_mfma_f32_16x16x32_bf16 v[2:5], v[198:201], v[230:233], v[2:5]
	s_setprio 0
	s_barrier
	s_add_i32 s66, 0, 0x18000
	v_add_u32_e32 v165, s66, v156
	s_add_i32 s67, 0, 0x1c000
	ds_read_b128 v[166:169], v165
	ds_read_b128 v[170:173], v165 offset:1024
	ds_read_b128 v[174:177], v165 offset:2048
	ds_read_b128 v[178:181], v165 offset:3072
	v_add_u32_e32 v165, s67, v156
	ds_read_b128 v[186:189], v165
	ds_read_b128 v[190:193], v165 offset:1024
	ds_read_b128 v[194:197], v165 offset:2048
	ds_read_b128 v[198:201], v165 offset:3072
	s_add_u32 s44, s44, 0x40000
	s_addc_u32 s45, s45, 0
	s_mov_b32 m0, s51
	v_lshl_add_u64 v[240:241], s[44:45], 0, v[136:137]
	ds_read_b128 v[202:205], v158 offset:32768
	ds_read_b128 v[206:209], v158 offset:33792
	ds_read_b128 v[210:213], v158 offset:34816
	ds_read_b128 v[214:217], v158 offset:35840
	ds_read_b128 v[218:221], v158 offset:36864
	ds_read_b128 v[222:225], v158 offset:37888
	ds_read_b128 v[226:229], v158 offset:38912
	ds_read_b128 v[230:233], v158 offset:39936
	global_load_lds_dwordx4 v[240:241], off
	v_lshl_add_u64 v[240:241], s[44:45], 0, v[132:133]
	s_mov_b32 m0, s52
	s_nop 0
	global_load_lds_dwordx4 v[240:241], off
	s_waitcnt vmcnt(8)
	s_waitcnt lgkmcnt(0)
	s_barrier
	s_setprio 1
	v_mfma_f32_16x16x32_bf16 v[126:129], v[166:169], v[202:205], v[126:129]
	v_mfma_f32_16x16x32_bf16 v[118:121], v[174:177], v[202:205], v[118:121]
	v_mfma_f32_16x16x32_bf16 v[110:113], v[166:169], v[210:213], v[110:113]
	v_mfma_f32_16x16x32_bf16 v[102:105], v[174:177], v[210:213], v[102:105]
	v_mfma_f32_16x16x32_bf16 v[94:97], v[166:169], v[218:221], v[94:97]
	v_mfma_f32_16x16x32_bf16 v[86:89], v[174:177], v[218:221], v[86:89]
	v_mfma_f32_16x16x32_bf16 v[78:81], v[166:169], v[226:229], v[78:81]
	v_mfma_f32_16x16x32_bf16 v[70:73], v[174:177], v[226:229], v[70:73]
	v_mfma_f32_16x16x32_bf16 v[126:129], v[170:173], v[206:209], v[126:129]
	v_mfma_f32_16x16x32_bf16 v[118:121], v[178:181], v[206:209], v[118:121]
	v_mfma_f32_16x16x32_bf16 v[110:113], v[170:173], v[214:217], v[110:113]
	v_mfma_f32_16x16x32_bf16 v[102:105], v[178:181], v[214:217], v[102:105]
	v_mfma_f32_16x16x32_bf16 v[94:97], v[170:173], v[222:225], v[94:97]
	v_mfma_f32_16x16x32_bf16 v[86:89], v[178:181], v[222:225], v[86:89]
	v_mfma_f32_16x16x32_bf16 v[78:81], v[170:173], v[230:233], v[78:81]
	v_mfma_f32_16x16x32_bf16 v[70:73], v[178:181], v[230:233], v[70:73]
	v_mfma_f32_16x16x32_bf16 v[122:125], v[186:189], v[202:205], v[122:125]
	v_mfma_f32_16x16x32_bf16 v[114:117], v[194:197], v[202:205], v[114:117]
	v_mfma_f32_16x16x32_bf16 v[106:109], v[186:189], v[210:213], v[106:109]
	v_mfma_f32_16x16x32_bf16 v[98:101], v[194:197], v[210:213], v[98:101]
	v_mfma_f32_16x16x32_bf16 v[90:93], v[186:189], v[218:221], v[90:93]
	v_mfma_f32_16x16x32_bf16 v[82:85], v[194:197], v[218:221], v[82:85]
	v_mfma_f32_16x16x32_bf16 v[74:77], v[186:189], v[226:229], v[74:77]
	v_mfma_f32_16x16x32_bf16 v[66:69], v[194:197], v[226:229], v[66:69]
	v_mfma_f32_16x16x32_bf16 v[122:125], v[190:193], v[206:209], v[122:125]
	v_mfma_f32_16x16x32_bf16 v[114:117], v[198:201], v[206:209], v[114:117]
	v_mfma_f32_16x16x32_bf16 v[106:109], v[190:193], v[214:217], v[106:109]
	v_mfma_f32_16x16x32_bf16 v[98:101], v[198:201], v[214:217], v[98:101]
	v_mfma_f32_16x16x32_bf16 v[90:93], v[190:193], v[222:225], v[90:93]
	v_mfma_f32_16x16x32_bf16 v[82:85], v[198:201], v[222:225], v[82:85]
	v_mfma_f32_16x16x32_bf16 v[74:77], v[190:193], v[230:233], v[74:77]
	v_mfma_f32_16x16x32_bf16 v[66:69], v[198:201], v[230:233], v[66:69]
	s_setprio 0
	s_barrier
; DI float fast_exp2(float x) { return __builtin_amdgcn_exp2f(x); }
; DI float fast_rcp(float x) { return __builtin_amdgcn_rcpf(x); }
; #define PG8_STAGE(bufoff, gbase, voff) do { _Pragma("unroll") for (int _i = 0; _i < 2; ++_i) \
;         __builtin_amdgcn_global_load_lds((const unsigned*)((const char*)(gbase) + (voff)[_i]), (LAS unsigned*)(lds + (bufoff) + ldsw + _i * 8192), 16, 0, 0); } while (0)
; #define PG8_LDA(dst, b, h) do { _Pragma("unroll") for (int m = 0; m < 4; ++m) _Pragma("unroll") for (int k = 0; k < 2; ++k) dst[m][k] = *(const LAS bf16x8*)(lds + PG8_SA(b, h) + aoff + m * 2048 + k * 1024); } while (0)
; #define PG8_MMA(ai, bj, At, Bt) do { __builtin_amdgcn_s_setprio(1); _Pragma("unroll") for (int m = 0; m < 4; ++m) _Pragma("unroll") for (int n = 0; n < 2; ++n) _Pragma("unroll") for (int k = 0; k < 2; ++k) \
;         acc[ai][bj][m][n] = __builtin_amdgcn_mfma_f32_16x16x32_bf16(Bt[n][k], At[m][k], acc[ai][bj][m][n], 0, 0, 0); __builtin_amdgcn_s_setprio(0); } while (0)
; #define PG8_WAIT_V(n) asm volatile("s_waitcnt vmcnt(" #n ")" ::: "memory")
; #define PG8_BAR __builtin_amdgcn_s_barrier()
; template <class Epi, class Sched>
; DI void gemm_phase(LAS unsigned char* lds, const Gemm g, const Sched& S, const Epi& E) {
;     ...
;             PG8_LDA(At, 1, 1); PG8_STAGE(PG8_SB(1, 0), b3, voffB); PG8_STAGE(PG8_SB(1, 1), b3 + hstepB, voffB); PG8_STAGE(PG8_SA(1, 0), a3, voffA);
;             PG8_WAIT_V(8); PG8_WAIT_L(0); PG8_BAR; PG8_MMA(1, 0, At, B0); PG8_MMA(1, 1, At, B1); PG8_BAR; PG8_SCHED;
;         }
;         if (wr == 0) PG8_BAR;
;     DI void operator()(Acc& acc, const pg8::Unit& u, int wr, int wc, int fr, int fq, const Pre& pr) const {
;         const int col = u.pn * 128 + wc * 32 + fq * 8;
; #pragma unroll
;         for (int ai = 0; ai < 2; ++ai)
; #pragma unroll
;             for (int m = 0; m < 4; ++m) {
;                 const int row = u.pm * 256 + ai * 128 + wr * 64 + m * 16 + fr;
;                 const float msq = msq_of(pr.v[ai * 4 + m]), nrl = -1.4426950408889634f * __builtin_amdgcn_rsqf(msq);
;                 f32x4 h[2];
; #pragma unroll
;                 for (int n = 0; n < 2; ++n)
; #pragma unroll
;                     for (int i = 0; i < 4; ++i) { const float ga = acc[ai][0][m][n][i], ua = acc[ai][1][m][n][i];
;                         const float e = fast_exp2(ga * nrl); h[n][i] = (ga * ua) * fast_rcp(__builtin_fmaf(e, msq, msq)); }
	s_add_i32 s44, s66, s46
	v_lshl_add_u64 v[182:183], v[182:183], 0, s[16:17]
	s_mov_b32 m0, s44
	ds_read_b128 v[202:205], v158 offset:49152
	ds_read_b128 v[206:209], v158 offset:50176
	ds_read_b128 v[210:213], v158 offset:51200
	ds_read_b128 v[214:217], v158 offset:52224
	ds_read_b128 v[218:221], v158 offset:53248
	ds_read_b128 v[222:225], v158 offset:54272
	ds_read_b128 v[226:229], v158 offset:55296
	ds_read_b128 v[230:233], v158 offset:56320
	global_load_lds_dwordx4 v[182:183], off
	s_add_i32 m0, s44, 0x2000
	s_add_u32 s42, s42, 0x40080
	v_lshl_add_u64 v[182:183], v[234:235], 0, s[16:17]
	s_addc_u32 s43, s43, 0
	s_add_i32 s44, s67, s46
	global_load_lds_dwordx4 v[182:183], off
	v_lshl_add_u64 v[182:183], s[42:43], 0, v[134:135]
	s_mov_b32 m0, s44
	s_nop 0
	global_load_lds_dwordx4 v[182:183], off
	v_lshl_add_u64 v[182:183], s[42:43], 0, v[130:131]
	s_add_i32 m0, s44, 0x2000
	s_nop 0
	global_load_lds_dwordx4 v[182:183], off
	v_lshl_add_u64 v[182:183], v[236:237], 0, s[16:17]
	s_mov_b32 m0, s54
	s_nop 0
	global_load_lds_dwordx4 v[182:183], off
	v_lshl_add_u64 v[182:183], v[238:239], 0, s[16:17]
	s_mov_b32 m0, s55
	s_nop 0
	global_load_lds_dwordx4 v[182:183], off
	s_waitcnt vmcnt(8)
	s_waitcnt lgkmcnt(0)
	s_barrier
	s_setprio 1
	v_mfma_f32_16x16x32_bf16 v[62:65], v[166:169], v[202:205], v[62:65]
	v_mfma_f32_16x16x32_bf16 v[54:57], v[174:177], v[202:205], v[54:57]
	v_mfma_f32_16x16x32_bf16 v[46:49], v[166:169], v[210:213], v[46:49]
	v_mfma_f32_16x16x32_bf16 v[38:41], v[174:177], v[210:213], v[38:41]
	v_mfma_f32_16x16x32_bf16 v[30:33], v[166:169], v[218:221], v[30:33]
	v_mfma_f32_16x16x32_bf16 v[22:25], v[174:177], v[218:221], v[22:25]
	v_mfma_f32_16x16x32_bf16 v[14:17], v[166:169], v[226:229], v[14:17]
	v_mfma_f32_16x16x32_bf16 v[6:9], v[174:177], v[226:229], v[6:9]
	v_mfma_f32_16x16x32_bf16 v[62:65], v[170:173], v[206:209], v[62:65]
	v_mfma_f32_16x16x32_bf16 v[54:57], v[178:181], v[206:209], v[54:57]
	v_mfma_f32_16x16x32_bf16 v[46:49], v[170:173], v[214:217], v[46:49]
	v_mfma_f32_16x16x32_bf16 v[38:41], v[178:181], v[214:217], v[38:41]
	v_mfma_f32_16x16x32_bf16 v[30:33], v[170:173], v[222:225], v[30:33]
	v_mfma_f32_16x16x32_bf16 v[22:25], v[178:181], v[222:225], v[22:25]
	v_mfma_f32_16x16x32_bf16 v[14:17], v[170:173], v[230:233], v[14:17]
	v_mfma_f32_16x16x32_bf16 v[6:9], v[178:181], v[230:233], v[6:9]
	v_mfma_f32_16x16x32_bf16 v[58:61], v[186:189], v[202:205], v[58:61]
	v_mfma_f32_16x16x32_bf16 v[50:53], v[194:197], v[202:205], v[50:53]
	v_mfma_f32_16x16x32_bf16 v[42:45], v[186:189], v[210:213], v[42:45]
	v_mfma_f32_16x16x32_bf16 v[34:37], v[194:197], v[210:213], v[34:37]
	v_mfma_f32_16x16x32_bf16 v[26:29], v[186:189], v[218:221], v[26:29]
	v_mfma_f32_16x16x32_bf16 v[18:21], v[194:197], v[218:221], v[18:21]
	v_mfma_f32_16x16x32_bf16 v[10:13], v[186:189], v[226:229], v[10:13]
	v_mfma_f32_16x16x32_bf16 v[2:5], v[194:197], v[226:229], v[2:5]
	v_mfma_f32_16x16x32_bf16 v[58:61], v[190:193], v[206:209], v[58:61]
	v_mfma_f32_16x16x32_bf16 v[50:53], v[198:201], v[206:209], v[50:53]
	v_mfma_f32_16x16x32_bf16 v[42:45], v[190:193], v[214:217], v[42:45]
	v_mfma_f32_16x16x32_bf16 v[34:37], v[198:201], v[214:217], v[34:37]
	v_mfma_f32_16x16x32_bf16 v[26:29], v[190:193], v[222:225], v[26:29]
	v_mfma_f32_16x16x32_bf16 v[18:21], v[198:201], v[222:225], v[18:21]
	v_mfma_f32_16x16x32_bf16 v[10:13], v[190:193], v[230:233], v[10:13]
	v_mfma_f32_16x16x32_bf16 v[2:5], v[198:201], v[230:233], v[2:5]
	s_setprio 0
	s_barrier
	s_add_i32 s65, s65, 2
	s_add_u32 s40, s40, 0x100
	s_addc_u32 s41, s41, 0
	s_add_u32 s63, s63, 0x100
	s_addc_u32 s64, s64, 0
	s_cmp_gt_u32 s65, 13
	s_cbranch_scc0 .LBB0_1234
	s_waitcnt vmcnt(0)
	s_mov_b32 s99, 1
	s_and_b64 vcc, s[10:11], s[4:5]
	s_cbranch_vccz .LBB0_1237
	s_barrier
.LBB0_1237:
	v_fmamk_f32 v186, v164, 0x3a800000, v159
	v_rsq_f32_e32 v189, v186
	v_lshl_or_b32 v202, s60, 7, v157
	v_lshlrev_b32_e32 v202, 1, v202
	v_mad_u32_u24 v194, v154, s59, v202
	v_mul_f32_e32 v188, 0xbfb8aa3b, v189
	v_fmamk_f32 v190, v163, 0x3a800000, v159
	v_rsq_f32_e32 v193, v190
	v_add_u32_e32 v195, 0x16000, v194
	v_add_u32_e32 v196, 0x2c000, v194
	v_add_u32_e32 v197, 0x42000, v194
	v_add_u32_e32 v198, 0xb0000, v194
	v_add_u32_e32 v199, 0xc6000, v194
	v_add_u32_e32 v200, 0xdc000, v194
	v_add_u32_e32 v201, 0xf2000, v194
	v_mul_f32_e32 v192, 0xbfb8aa3b, v193
	v_pk_mul_f32 v[122:123], v[126:127], v[122:123]
	v_pk_mul_f32 v[124:125], v[128:129], v[124:125]
	v_pk_mul_f32 v[114:115], v[118:119], v[114:115]
	v_pk_mul_f32 v[116:117], v[120:121], v[116:117]
	v_pk_mul_f32 v[126:127], v[126:127], v[188:189] op_sel_hi:[1,0]
	v_pk_mul_f32 v[128:129], v[128:129], v[188:189] op_sel_hi:[1,0]
	v_pk_mul_f32 v[118:119], v[118:119], v[188:189] op_sel_hi:[1,0]
	v_pk_mul_f32 v[120:121], v[120:121], v[188:189] op_sel_hi:[1,0]
	v_exp_f32_e32 v126, v126
	v_exp_f32_e32 v127, v127
	v_exp_f32_e32 v128, v128
	v_exp_f32_e32 v129, v129
	v_exp_f32_e32 v118, v118
	v_exp_f32_e32 v119, v119
	v_exp_f32_e32 v120, v120
	v_exp_f32_e32 v121, v121
	v_pk_fma_f32 v[126:127], v[126:127], v[186:187], v[186:187] op_sel_hi:[1,0,0]
	v_pk_fma_f32 v[128:129], v[128:129], v[186:187], v[186:187] op_sel_hi:[1,0,0]
	v_pk_fma_f32 v[118:119], v[118:119], v[186:187], v[186:187] op_sel_hi:[1,0,0]
	v_pk_fma_f32 v[120:121], v[120:121], v[186:187], v[186:187] op_sel_hi:[1,0,0]
	v_rcp_f32_e32 v126, v126
	v_rcp_f32_e32 v127, v127
	v_rcp_f32_e32 v128, v128
	v_rcp_f32_e32 v129, v129
	v_rcp_f32_e32 v118, v118
	v_rcp_f32_e32 v119, v119
	v_rcp_f32_e32 v120, v120
	v_rcp_f32_e32 v121, v121
	v_fmamk_f32 v186, v162, 0x3a800000, v159
	v_rsq_f32_e32 v189, v186
	v_pk_mul_f32 v[122:123], v[126:127], v[122:123]
; DI float fast_exp2(float x) { return __builtin_amdgcn_exp2f(x); }
; DI float fast_rcp(float x) { return __builtin_amdgcn_rcpf(x); }
;     DI void operator()(Acc& acc, const pg8::Unit& u, int wr, int wc, int fr, int fq, const Pre& pr) const {
;         const int col = u.pn * 128 + wc * 32 + fq * 8;
; #pragma unroll
;         for (int ai = 0; ai < 2; ++ai)
; #pragma unroll
;             for (int m = 0; m < 4; ++m) {
;                 const int row = u.pm * 256 + ai * 128 + wr * 64 + m * 16 + fr;
;                 const float msq = msq_of(pr.v[ai * 4 + m]), nrl = -1.4426950408889634f * __builtin_amdgcn_rsqf(msq);
;                 f32x4 h[2];
; #pragma unroll
;                 for (int n = 0; n < 2; ++n)
; #pragma unroll
;                     for (int i = 0; i < 4; ++i) { const float ga = acc[ai][0][m][n][i], ua = acc[ai][1][m][n][i];
;                         const float e = fast_exp2(ga * nrl); h[n][i] = (ga * ua) * fast_rcp(__builtin_fmaf(e, msq, msq)); }
;                 store8(H + (size_t)row * FF + col, h[0], h[1]);
;             }
	v_pk_mul_f32 v[124:125], v[128:129], v[124:125]
	v_pk_mul_f32 v[114:115], v[118:119], v[114:115]
	v_pk_mul_f32 v[116:117], v[120:121], v[116:117]
	v_cvt_pk_bf16_f32 v126, v122, v123
	v_cvt_pk_bf16_f32 v127, v124, v125
	v_cvt_pk_bf16_f32 v128, v114, v115
	v_cvt_pk_bf16_f32 v129, v116, v117
	v_mul_f32_e32 v188, 0xbfb8aa3b, v189
	v_pk_mul_f32 v[106:107], v[110:111], v[106:107]
	v_pk_mul_f32 v[108:109], v[112:113], v[108:109]
	v_pk_mul_f32 v[98:99], v[102:103], v[98:99]
	v_pk_mul_f32 v[100:101], v[104:105], v[100:101]
	v_pk_mul_f32 v[110:111], v[110:111], v[192:193] op_sel_hi:[1,0]
	v_pk_mul_f32 v[112:113], v[112:113], v[192:193] op_sel_hi:[1,0]
	v_pk_mul_f32 v[102:103], v[102:103], v[192:193] op_sel_hi:[1,0]
	v_pk_mul_f32 v[104:105], v[104:105], v[192:193] op_sel_hi:[1,0]
	v_exp_f32_e32 v110, v110
	v_exp_f32_e32 v111, v111
	v_exp_f32_e32 v112, v112
	v_exp_f32_e32 v113, v113
	v_exp_f32_e32 v102, v102
	v_exp_f32_e32 v103, v103
	v_exp_f32_e32 v104, v104
	v_exp_f32_e32 v105, v105
	global_store_dwordx4 v194, v[126:129], s[12:13]
	v_pk_fma_f32 v[110:111], v[110:111], v[190:191], v[190:191] op_sel_hi:[1,0,0]
	v_pk_fma_f32 v[112:113], v[112:113], v[190:191], v[190:191] op_sel_hi:[1,0,0]
	v_pk_fma_f32 v[102:103], v[102:103], v[190:191], v[190:191] op_sel_hi:[1,0,0]
	v_pk_fma_f32 v[104:105], v[104:105], v[190:191], v[190:191] op_sel_hi:[1,0,0]
	v_rcp_f32_e32 v110, v110
	v_rcp_f32_e32 v111, v111
	v_rcp_f32_e32 v112, v112
	v_rcp_f32_e32 v113, v113
	v_rcp_f32_e32 v102, v102
	v_rcp_f32_e32 v103, v103
	v_rcp_f32_e32 v104, v104
	v_rcp_f32_e32 v105, v105
	v_fmamk_f32 v190, v155, 0x3a800000, v159
	v_rsq_f32_e32 v193, v190
	v_pk_mul_f32 v[106:107], v[110:111], v[106:107]
	v_pk_mul_f32 v[108:109], v[112:113], v[108:109]
	v_pk_mul_f32 v[98:99], v[102:103], v[98:99]
	v_pk_mul_f32 v[100:101], v[104:105], v[100:101]
	v_cvt_pk_bf16_f32 v110, v106, v107
	v_cvt_pk_bf16_f32 v111, v108, v109
	v_cvt_pk_bf16_f32 v112, v98, v99
	v_cvt_pk_bf16_f32 v113, v100, v101
	v_mul_f32_e32 v192, 0xbfb8aa3b, v193
	v_pk_mul_f32 v[90:91], v[94:95], v[90:91]
	v_pk_mul_f32 v[92:93], v[96:97], v[92:93]
	v_pk_mul_f32 v[82:83], v[86:87], v[82:83]
	v_pk_mul_f32 v[84:85], v[88:89], v[84:85]
	v_pk_mul_f32 v[94:95], v[94:95], v[188:189] op_sel_hi:[1,0]
	v_pk_mul_f32 v[96:97], v[96:97], v[188:189] op_sel_hi:[1,0]
	v_pk_mul_f32 v[86:87], v[86:87], v[188:189] op_sel_hi:[1,0]
	v_pk_mul_f32 v[88:89], v[88:89], v[188:189] op_sel_hi:[1,0]
	v_exp_f32_e32 v94, v94
	v_exp_f32_e32 v95, v95
	v_exp_f32_e32 v96, v96
	v_exp_f32_e32 v97, v97
	v_exp_f32_e32 v86, v86
	v_exp_f32_e32 v87, v87
	v_exp_f32_e32 v88, v88
	v_exp_f32_e32 v89, v89
	global_store_dwordx4 v195, v[110:113], s[12:13]
	v_pk_fma_f32 v[94:95], v[94:95], v[186:187], v[186:187] op_sel_hi:[1,0,0]
	v_pk_fma_f32 v[96:97], v[96:97], v[186:187], v[186:187] op_sel_hi:[1,0,0]
	v_pk_fma_f32 v[86:87], v[86:87], v[186:187], v[186:187] op_sel_hi:[1,0,0]
	v_pk_fma_f32 v[88:89], v[88:89], v[186:187], v[186:187] op_sel_hi:[1,0,0]
	v_rcp_f32_e32 v94, v94
	v_rcp_f32_e32 v95, v95
	v_rcp_f32_e32 v96, v96
	v_rcp_f32_e32 v97, v97
	v_rcp_f32_e32 v86, v86
	v_rcp_f32_e32 v87, v87
	v_rcp_f32_e32 v88, v88
	v_rcp_f32_e32 v89, v89
	v_fmamk_f32 v186, v153, 0x3a800000, v159
	v_rsq_f32_e32 v189, v186
	v_pk_mul_f32 v[90:91], v[94:95], v[90:91]
	v_pk_mul_f32 v[92:93], v[96:97], v[92:93]
	v_pk_mul_f32 v[82:83], v[86:87], v[82:83]
	v_pk_mul_f32 v[84:85], v[88:89], v[84:85]
	v_cvt_pk_bf16_f32 v94, v90, v91
	v_cvt_pk_bf16_f32 v95, v92, v93
	v_cvt_pk_bf16_f32 v96, v82, v83
	v_cvt_pk_bf16_f32 v97, v84, v85
	v_mul_f32_e32 v188, 0xbfb8aa3b, v189
	v_pk_mul_f32 v[74:75], v[78:79], v[74:75]
	v_pk_mul_f32 v[76:77], v[80:81], v[76:77]
	v_pk_mul_f32 v[66:67], v[70:71], v[66:67]
	v_pk_mul_f32 v[68:69], v[72:73], v[68:69]
	v_pk_mul_f32 v[78:79], v[78:79], v[192:193] op_sel_hi:[1,0]
	v_pk_mul_f32 v[80:81], v[80:81], v[192:193] op_sel_hi:[1,0]
	v_pk_mul_f32 v[70:71], v[70:71], v[192:193] op_sel_hi:[1,0]
	v_pk_mul_f32 v[72:73], v[72:73], v[192:193] op_sel_hi:[1,0]
	v_exp_f32_e32 v78, v78
	v_exp_f32_e32 v79, v79
	v_exp_f32_e32 v80, v80
	v_exp_f32_e32 v81, v81
	v_exp_f32_e32 v70, v70
	v_exp_f32_e32 v71, v71
	v_exp_f32_e32 v72, v72
	v_exp_f32_e32 v73, v73
	global_store_dwordx4 v196, v[94:97], s[12:13]
	v_pk_fma_f32 v[78:79], v[78:79], v[190:191], v[190:191] op_sel_hi:[1,0,0]
	v_pk_fma_f32 v[80:81], v[80:81], v[190:191], v[190:191] op_sel_hi:[1,0,0]
	v_pk_fma_f32 v[70:71], v[70:71], v[190:191], v[190:191] op_sel_hi:[1,0,0]
	v_pk_fma_f32 v[72:73], v[72:73], v[190:191], v[190:191] op_sel_hi:[1,0,0]
	v_rcp_f32_e32 v78, v78
	v_rcp_f32_e32 v79, v79
	v_rcp_f32_e32 v80, v80
	v_rcp_f32_e32 v81, v81
	v_rcp_f32_e32 v70, v70
	v_rcp_f32_e32 v71, v71
	v_rcp_f32_e32 v72, v72
	v_rcp_f32_e32 v73, v73
	v_fmamk_f32 v190, v151, 0x3a800000, v159
	v_rsq_f32_e32 v193, v190
	v_pk_mul_f32 v[74:75], v[78:79], v[74:75]
	v_pk_mul_f32 v[76:77], v[80:81], v[76:77]
	v_pk_mul_f32 v[66:67], v[70:71], v[66:67]
	v_pk_mul_f32 v[68:69], v[72:73], v[68:69]
	v_cvt_pk_bf16_f32 v78, v74, v75
	v_cvt_pk_bf16_f32 v79, v76, v77
	v_cvt_pk_bf16_f32 v80, v66, v67
	v_cvt_pk_bf16_f32 v81, v68, v69
	v_mul_f32_e32 v192, 0xbfb8aa3b, v193
	v_pk_mul_f32 v[58:59], v[62:63], v[58:59]
	v_pk_mul_f32 v[60:61], v[64:65], v[60:61]
	v_pk_mul_f32 v[50:51], v[54:55], v[50:51]
	v_pk_mul_f32 v[52:53], v[56:57], v[52:53]
	v_pk_mul_f32 v[62:63], v[62:63], v[188:189] op_sel_hi:[1,0]
	v_pk_mul_f32 v[64:65], v[64:65], v[188:189] op_sel_hi:[1,0]
	v_pk_mul_f32 v[54:55], v[54:55], v[188:189] op_sel_hi:[1,0]
	v_pk_mul_f32 v[56:57], v[56:57], v[188:189] op_sel_hi:[1,0]
	v_exp_f32_e32 v62, v62
	v_exp_f32_e32 v63, v63
	v_exp_f32_e32 v64, v64
	v_exp_f32_e32 v65, v65
; DI float fast_exp2(float x) { return __builtin_amdgcn_exp2f(x); }
; DI float fast_rcp(float x) { return __builtin_amdgcn_rcpf(x); }
; #define PG8_BAR __builtin_amdgcn_s_barrier()
;     DI void pre(Pre& pr, const pg8::Unit& u, int wr, int fr) const { load_rows(pr, ssq, u, wr, fr); }
;     DI void pre(Pre& pr, const pg8::Unit& u, int wr, int fr) const { load_rows(pr, ssq, u, wr, fr); }
; template <class Epi, class Sched>
; DI void gemm_phase(LAS unsigned char* lds, const Gemm g, const Sched& S, const Epi& E) {
;     ...
;         if (wr == 0) PG8_BAR;
;         E(acc, cur, wr, wc, fr, fq, pre);
;         if (!has_next) break;
;         if (!(Epi::CHAIN && cur.src == 0)) {
; #pragma unroll
;             for (int a = 0; a < 2; ++a)
; #pragma unroll
;                 for (int b = 0; b < 2; ++b)
; #pragma unroll
;                     for (int m = 0; m < 4; ++m)
; #pragma unroll
;                         for (int n = 0; n < 2; ++n) acc[a][b][m][n] = (f32x4){0.f, 0.f, 0.f, 0.f};
;         }
;         cur = nxt; cA = nA; cB = nB; ++ui;
;         if (wr == 1) PG8_BAR;
;     DI void operator()(Acc& acc, const pg8::Unit& u, int wr, int wc, int fr, int fq, const Pre& pr) const {
;         const int col = u.pn * 128 + wc * 32 + fq * 8;
; #pragma unroll
;         for (int ai = 0; ai < 2; ++ai)
; #pragma unroll
;             for (int m = 0; m < 4; ++m) {
;                 const int row = u.pm * 256 + ai * 128 + wr * 64 + m * 16 + fr;
;                 const float msq = msq_of(pr.v[ai * 4 + m]), nrl = -1.4426950408889634f * __builtin_amdgcn_rsqf(msq);
;                 f32x4 h[2];
; #pragma unroll
;                 for (int n = 0; n < 2; ++n)
; #pragma unroll
;                     for (int i = 0; i < 4; ++i) { const float ga = acc[ai][0][m][n][i], ua = acc[ai][1][m][n][i];
;                         const float e = fast_exp2(ga * nrl); h[n][i] = (ga * ua) * fast_rcp(__builtin_fmaf(e, msq, msq)); }
;                 store8(H + (size_t)row * FF + col, h[0], h[1]);
;             }
	v_exp_f32_e32 v54, v54
	v_exp_f32_e32 v55, v55
	v_exp_f32_e32 v56, v56
	v_exp_f32_e32 v57, v57
	global_store_dwordx4 v197, v[78:81], s[12:13]
	v_pk_fma_f32 v[62:63], v[62:63], v[186:187], v[186:187] op_sel_hi:[1,0,0]
	v_pk_fma_f32 v[64:65], v[64:65], v[186:187], v[186:187] op_sel_hi:[1,0,0]
	v_pk_fma_f32 v[54:55], v[54:55], v[186:187], v[186:187] op_sel_hi:[1,0,0]
	v_pk_fma_f32 v[56:57], v[56:57], v[186:187], v[186:187] op_sel_hi:[1,0,0]
	v_rcp_f32_e32 v62, v62
	v_rcp_f32_e32 v63, v63
	v_rcp_f32_e32 v64, v64
	v_rcp_f32_e32 v65, v65
	v_rcp_f32_e32 v54, v54
	v_rcp_f32_e32 v55, v55
	v_rcp_f32_e32 v56, v56
	v_rcp_f32_e32 v57, v57
	v_fmamk_f32 v186, v149, 0x3a800000, v159
	v_rsq_f32_e32 v189, v186
	v_pk_mul_f32 v[58:59], v[62:63], v[58:59]
	v_pk_mul_f32 v[60:61], v[64:65], v[60:61]
	v_pk_mul_f32 v[50:51], v[54:55], v[50:51]
	v_pk_mul_f32 v[52:53], v[56:57], v[52:53]
	v_cvt_pk_bf16_f32 v62, v58, v59
	v_cvt_pk_bf16_f32 v63, v60, v61
	v_cvt_pk_bf16_f32 v64, v50, v51
	v_cvt_pk_bf16_f32 v65, v52, v53
	v_mul_f32_e32 v188, 0xbfb8aa3b, v189
	v_pk_mul_f32 v[42:43], v[46:47], v[42:43]
	v_pk_mul_f32 v[44:45], v[48:49], v[44:45]
	v_pk_mul_f32 v[34:35], v[38:39], v[34:35]
	v_pk_mul_f32 v[36:37], v[40:41], v[36:37]
	v_pk_mul_f32 v[46:47], v[46:47], v[192:193] op_sel_hi:[1,0]
	v_pk_mul_f32 v[48:49], v[48:49], v[192:193] op_sel_hi:[1,0]
	v_pk_mul_f32 v[38:39], v[38:39], v[192:193] op_sel_hi:[1,0]
	v_pk_mul_f32 v[40:41], v[40:41], v[192:193] op_sel_hi:[1,0]
	v_exp_f32_e32 v46, v46
	v_exp_f32_e32 v47, v47
	v_exp_f32_e32 v48, v48
	v_exp_f32_e32 v49, v49
	v_exp_f32_e32 v38, v38
	v_exp_f32_e32 v39, v39
	v_exp_f32_e32 v40, v40
	v_exp_f32_e32 v41, v41
	global_store_dwordx4 v198, v[62:65], s[12:13]
	v_pk_fma_f32 v[46:47], v[46:47], v[190:191], v[190:191] op_sel_hi:[1,0,0]
	v_pk_fma_f32 v[48:49], v[48:49], v[190:191], v[190:191] op_sel_hi:[1,0,0]
	v_pk_fma_f32 v[38:39], v[38:39], v[190:191], v[190:191] op_sel_hi:[1,0,0]
	v_pk_fma_f32 v[40:41], v[40:41], v[190:191], v[190:191] op_sel_hi:[1,0,0]
	v_rcp_f32_e32 v46, v46
	v_rcp_f32_e32 v47, v47
	v_rcp_f32_e32 v48, v48
	v_rcp_f32_e32 v49, v49
	v_rcp_f32_e32 v38, v38
	v_rcp_f32_e32 v39, v39
	v_rcp_f32_e32 v40, v40
	v_rcp_f32_e32 v41, v41
	v_fmamk_f32 v190, v147, 0x3a800000, v159
	v_rsq_f32_e32 v193, v190
	v_pk_mul_f32 v[42:43], v[46:47], v[42:43]
	v_pk_mul_f32 v[44:45], v[48:49], v[44:45]
	v_pk_mul_f32 v[34:35], v[38:39], v[34:35]
	v_pk_mul_f32 v[36:37], v[40:41], v[36:37]
	v_cvt_pk_bf16_f32 v46, v42, v43
	v_cvt_pk_bf16_f32 v47, v44, v45
	v_cvt_pk_bf16_f32 v48, v34, v35
	v_cvt_pk_bf16_f32 v49, v36, v37
	v_mul_f32_e32 v192, 0xbfb8aa3b, v193
	v_pk_mul_f32 v[26:27], v[30:31], v[26:27]
	v_pk_mul_f32 v[28:29], v[32:33], v[28:29]
	v_pk_mul_f32 v[18:19], v[22:23], v[18:19]
	v_pk_mul_f32 v[20:21], v[24:25], v[20:21]
	v_pk_mul_f32 v[30:31], v[30:31], v[188:189] op_sel_hi:[1,0]
	v_pk_mul_f32 v[32:33], v[32:33], v[188:189] op_sel_hi:[1,0]
	v_pk_mul_f32 v[22:23], v[22:23], v[188:189] op_sel_hi:[1,0]
	v_pk_mul_f32 v[24:25], v[24:25], v[188:189] op_sel_hi:[1,0]
	v_exp_f32_e32 v30, v30
	v_exp_f32_e32 v31, v31
	v_exp_f32_e32 v32, v32
	v_exp_f32_e32 v33, v33
	v_exp_f32_e32 v22, v22
	v_exp_f32_e32 v23, v23
	v_exp_f32_e32 v24, v24
	v_exp_f32_e32 v25, v25
	global_store_dwordx4 v199, v[46:49], s[12:13]
	v_pk_fma_f32 v[30:31], v[30:31], v[186:187], v[186:187] op_sel_hi:[1,0,0]
	v_pk_fma_f32 v[32:33], v[32:33], v[186:187], v[186:187] op_sel_hi:[1,0,0]
	v_pk_fma_f32 v[22:23], v[22:23], v[186:187], v[186:187] op_sel_hi:[1,0,0]
	v_pk_fma_f32 v[24:25], v[24:25], v[186:187], v[186:187] op_sel_hi:[1,0,0]
	v_rcp_f32_e32 v30, v30
	v_rcp_f32_e32 v31, v31
	v_rcp_f32_e32 v32, v32
	v_rcp_f32_e32 v33, v33
	v_rcp_f32_e32 v22, v22
	v_rcp_f32_e32 v23, v23
	v_rcp_f32_e32 v24, v24
	v_rcp_f32_e32 v25, v25
	v_pk_mul_f32 v[26:27], v[30:31], v[26:27]
	v_pk_mul_f32 v[28:29], v[32:33], v[28:29]
	v_pk_mul_f32 v[18:19], v[22:23], v[18:19]
	v_pk_mul_f32 v[20:21], v[24:25], v[20:21]
	v_cvt_pk_bf16_f32 v30, v26, v27
	v_cvt_pk_bf16_f32 v31, v28, v29
	v_cvt_pk_bf16_f32 v32, v18, v19
	v_cvt_pk_bf16_f32 v33, v20, v21
	v_pk_mul_f32 v[10:11], v[14:15], v[10:11]
	v_pk_mul_f32 v[12:13], v[16:17], v[12:13]
	v_pk_mul_f32 v[2:3], v[6:7], v[2:3]
	v_pk_mul_f32 v[4:5], v[8:9], v[4:5]
	v_pk_mul_f32 v[14:15], v[14:15], v[192:193] op_sel_hi:[1,0]
	v_pk_mul_f32 v[16:17], v[16:17], v[192:193] op_sel_hi:[1,0]
	v_pk_mul_f32 v[6:7], v[6:7], v[192:193] op_sel_hi:[1,0]
	v_pk_mul_f32 v[8:9], v[8:9], v[192:193] op_sel_hi:[1,0]
	v_exp_f32_e32 v14, v14
	v_exp_f32_e32 v15, v15
	v_exp_f32_e32 v16, v16
	v_exp_f32_e32 v17, v17
	v_exp_f32_e32 v6, v6
	v_exp_f32_e32 v7, v7
	v_exp_f32_e32 v8, v8
	v_exp_f32_e32 v9, v9
	global_store_dwordx4 v200, v[30:33], s[12:13]
	v_pk_fma_f32 v[14:15], v[14:15], v[190:191], v[190:191] op_sel_hi:[1,0,0]
	v_pk_fma_f32 v[16:17], v[16:17], v[190:191], v[190:191] op_sel_hi:[1,0,0]
	v_pk_fma_f32 v[6:7], v[6:7], v[190:191], v[190:191] op_sel_hi:[1,0,0]
	v_pk_fma_f32 v[8:9], v[8:9], v[190:191], v[190:191] op_sel_hi:[1,0,0]
	v_rcp_f32_e32 v14, v14
	v_rcp_f32_e32 v15, v15
	v_rcp_f32_e32 v16, v16
	v_rcp_f32_e32 v17, v17
	v_rcp_f32_e32 v6, v6
	v_rcp_f32_e32 v7, v7
	v_rcp_f32_e32 v8, v8
	v_rcp_f32_e32 v9, v9
	v_pk_mul_f32 v[10:11], v[14:15], v[10:11]
	v_pk_mul_f32 v[12:13], v[16:17], v[12:13]
	v_pk_mul_f32 v[2:3], v[6:7], v[2:3]
	v_pk_mul_f32 v[4:5], v[8:9], v[4:5]
	v_cvt_pk_bf16_f32 v14, v10, v11
	v_cvt_pk_bf16_f32 v15, v12, v13
	v_cvt_pk_bf16_f32 v16, v2, v3
	v_cvt_pk_bf16_f32 v17, v4, v5
	s_and_b64 vcc, exec, s[18:19]
	s_cbranch_vccz .Lgu9_noalign
	s_barrier
.Lgu9_noalign:
	s_andn2_b64 vcc, exec, s[4:5]
	s_mov_b64 s[4:5], -1
	global_store_dwordx4 v201, v[14:17], s[12:13]
	s_cbranch_vccnz .LBB0_1230
	s_branch .LBB0_1229
